# RES1/RES2/FIN GEMM epilogues: residual tile prefetched before K-loop, batched LDS reads, DPP row-sum reduction
# speedup vs baseline: 1.0151x; 1.0151x over previous
.LBB0_83:
	v_and_b32_e32 v0, 64, v74
	v_lshl_or_b32 v66, v76, 2, v77
	s_movk_i32 s23, 0x210
	v_lshl_add_u32 v0, v0, 2, 16
	v_lshlrev_b32_e32 v67, 2, v75
	v_mul_lo_u32 v66, v66, s23
	v_add3_u32 v0, v0, v67, v66
	ds_write2_b32 v0, v34, v6 offset1:16
	ds_write2_b32 v0, v35, v7 offset0:132 offset1:148
	v_add_u32_e32 v6, 0x400, v0
	ds_write2_b32 v6, v36, v8 offset0:8 offset1:24
	ds_write2_b32 v6, v37, v9 offset0:140 offset1:156
	ds_write2_b32 v0, v42, v10 offset0:32 offset1:48
	ds_write2_b32 v0, v43, v11 offset0:164 offset1:180
	ds_write2_b32 v6, v44, v12 offset0:40 offset1:56
	ds_write2_b32 v6, v45, v13 offset0:172 offset1:188
	v_add_u32_e32 v6, 0x2000, v0
	v_add_u32_e32 v7, 0x2400, v0
	ds_write2_b32 v6, v38, v14 offset0:64 offset1:80
	ds_write2_b32 v6, v39, v15 offset0:196 offset1:212
	ds_write2_b32 v7, v40, v16 offset0:72 offset1:88
	ds_write2_b32 v7, v41, v17 offset0:204 offset1:220
	ds_write2_b32 v6, v46, v22 offset0:96 offset1:112
	ds_write2_b32 v6, v47, v23 offset0:228 offset1:244
	ds_write2_b32 v7, v48, v24 offset0:104 offset1:120
	ds_write2_b32 v7, v49, v25 offset0:236 offset1:252
	v_add_u32_e32 v6, 0x4000, v0
	v_add_u32_e32 v7, 0x4400, v0
	v_add_u32_e32 v8, 0x4800, v0
	ds_write2_b32 v6, v50, v18 offset0:128 offset1:144
	ds_write2_b32 v7, v51, v19 offset0:4 offset1:20
	ds_write2_b32 v7, v52, v20 offset0:136 offset1:152
	ds_write2_b32 v8, v53, v21 offset0:12 offset1:28
	ds_write2_b32 v6, v54, v30 offset0:160 offset1:176
	ds_write2_b32 v7, v55, v31 offset0:36 offset1:52
	ds_write2_b32 v7, v56, v32 offset0:168 offset1:184
	ds_write2_b32 v8, v57, v33 offset0:44 offset1:60
	v_add_u32_e32 v6, 0x6000, v0
	v_add_u32_e32 v7, 0x6400, v0
	v_add_u32_e32 v0, 0x6800, v0
	ds_write2_b32 v6, v58, v26 offset0:192 offset1:208
	ds_write2_b32 v7, v59, v27 offset0:68 offset1:84
	ds_write2_b32 v7, v60, v28 offset0:200 offset1:216
	ds_write2_b32 v0, v61, v29 offset0:76 offset1:92
	ds_write2_b32 v6, v62, v2 offset0:224 offset1:240
	ds_write2_b32 v7, v63, v3 offset0:100 offset1:116
	ds_write2_b32 v7, v64, v4 offset0:232 offset1:248
	ds_write2_b32 v0, v65, v5 offset0:108 offset1:124
	s_load_dwordx2 s[44:45], s[12:13], 0x100
	s_waitcnt vmcnt(0) lgkmcnt(0)
	s_barrier
	s_lshl_b32 s24, s22, 13
	s_lshl_b32 s25, s40, 2
	s_add_i32 s24, s24, s25
	s_add_u32 s44, s44, s24
	s_addc_u32 s45, s45, 0
	v_lshrrev_b32_e32 v66, 5, v131
	v_and_b32_e32 v67, 31, v131
	s_movk_i32 s25, 0x210
	v_lshlrev_b32_e32 v68, 4, v67
	v_mad_u32_u24 v69, v66, s25, v68
	v_add_u32_e32 v69, 16, v69
	ds_read_b128 v[2:5], v69
	ds_read_b128 v[6:9], v69 offset:4224
	ds_read_b128 v[10:13], v69 offset:8448
	ds_read_b128 v[14:17], v69 offset:12672
	ds_read_b128 v[18:21], v69 offset:16896
	ds_read_b128 v[22:25], v69 offset:21120
	ds_read_b128 v[26:29], v69 offset:25344
	ds_read_b128 v[30:33], v69 offset:29568
	ds_read_b128 v[34:37], v69 offset:33792
	ds_read_b128 v[38:41], v69 offset:38016
	ds_read_b128 v[42:45], v69 offset:42240
	ds_read_b128 v[46:49], v69 offset:46464
	ds_read_b128 v[50:53], v69 offset:50688
	ds_read_b128 v[54:57], v69 offset:54912
	ds_read_b128 v[58:61], v69 offset:59136
	ds_read_b128 v[62:65], v69 offset:63360
	s_waitcnt lgkmcnt(15)
	v_pk_add_f32 v[2:3], v[2:3], v[180:181]
	v_pk_add_f32 v[4:5], v[4:5], v[182:183]
	global_store_dwordx4 v252, v[2:5], s[44:45]
	s_add_u32 s44, s44, 0x10000
	s_addc_u32 s45, s45, 0
	s_waitcnt lgkmcnt(14)
	v_pk_add_f32 v[6:7], v[6:7], v[184:185]
	v_pk_add_f32 v[8:9], v[8:9], v[186:187]
	global_store_dwordx4 v252, v[6:9], s[44:45]
	s_add_u32 s44, s44, 0x10000
	s_addc_u32 s45, s45, 0
	s_waitcnt lgkmcnt(13)
	v_pk_add_f32 v[10:11], v[10:11], v[188:189]
	v_pk_add_f32 v[12:13], v[12:13], v[190:191]
	global_store_dwordx4 v252, v[10:13], s[44:45]
	s_add_u32 s44, s44, 0x10000
	s_addc_u32 s45, s45, 0
	s_waitcnt lgkmcnt(12)
	v_pk_add_f32 v[14:15], v[14:15], v[196:197]
	v_pk_add_f32 v[16:17], v[16:17], v[198:199]
	global_store_dwordx4 v252, v[14:17], s[44:45]
	s_add_u32 s44, s44, 0x10000
	s_addc_u32 s45, s45, 0
	s_waitcnt lgkmcnt(11)
	v_pk_add_f32 v[18:19], v[18:19], v[200:201]
	v_pk_add_f32 v[20:21], v[20:21], v[202:203]
	global_store_dwordx4 v252, v[18:21], s[44:45]
	s_add_u32 s44, s44, 0x10000
	s_addc_u32 s45, s45, 0
	s_waitcnt lgkmcnt(10)
	v_pk_add_f32 v[22:23], v[22:23], v[204:205]
	v_pk_add_f32 v[24:25], v[24:25], v[206:207]
	global_store_dwordx4 v252, v[22:25], s[44:45]
	s_add_u32 s44, s44, 0x10000
	s_addc_u32 s45, s45, 0
	s_waitcnt lgkmcnt(9)
	v_pk_add_f32 v[26:27], v[26:27], v[212:213]
	v_pk_add_f32 v[28:29], v[28:29], v[214:215]
	global_store_dwordx4 v252, v[26:29], s[44:45]
	s_add_u32 s44, s44, 0x10000
	s_addc_u32 s45, s45, 0
	s_waitcnt lgkmcnt(8)
	v_pk_add_f32 v[30:31], v[30:31], v[216:217]
	v_pk_add_f32 v[32:33], v[32:33], v[218:219]
	global_store_dwordx4 v252, v[30:33], s[44:45]
	s_add_u32 s44, s44, 0x10000
	s_addc_u32 s45, s45, 0
	s_waitcnt lgkmcnt(7)
	v_pk_add_f32 v[34:35], v[34:35], v[220:221]
	v_pk_add_f32 v[36:37], v[36:37], v[222:223]
	global_store_dwordx4 v252, v[34:37], s[44:45]
	s_add_u32 s44, s44, 0x10000
	s_addc_u32 s45, s45, 0
	s_waitcnt lgkmcnt(6)
	v_pk_add_f32 v[38:39], v[38:39], v[224:225]
	v_pk_add_f32 v[40:41], v[40:41], v[226:227]
	global_store_dwordx4 v252, v[38:41], s[44:45]
	s_add_u32 s44, s44, 0x10000
	s_addc_u32 s45, s45, 0
	s_waitcnt lgkmcnt(5)
	v_pk_add_f32 v[42:43], v[42:43], v[228:229]
	v_pk_add_f32 v[44:45], v[44:45], v[230:231]
	global_store_dwordx4 v252, v[42:45], s[44:45]
	s_add_u32 s44, s44, 0x10000
	s_addc_u32 s45, s45, 0
	s_waitcnt lgkmcnt(4)
	v_pk_add_f32 v[46:47], v[46:47], v[232:233]
	v_pk_add_f32 v[48:49], v[48:49], v[234:235]
	global_store_dwordx4 v252, v[46:49], s[44:45]
	s_add_u32 s44, s44, 0x10000
	s_addc_u32 s45, s45, 0
	s_waitcnt lgkmcnt(3)
	v_pk_add_f32 v[50:51], v[50:51], v[236:237]
	v_pk_add_f32 v[52:53], v[52:53], v[238:239]
	global_store_dwordx4 v252, v[50:53], s[44:45]
	s_add_u32 s44, s44, 0x10000
	s_addc_u32 s45, s45, 0
	s_waitcnt lgkmcnt(2)
	v_pk_add_f32 v[54:55], v[54:55], v[240:241]
	v_pk_add_f32 v[56:57], v[56:57], v[242:243]
	global_store_dwordx4 v252, v[54:57], s[44:45]
	s_add_u32 s44, s44, 0x10000
	s_addc_u32 s45, s45, 0
	s_waitcnt lgkmcnt(1)
	v_pk_add_f32 v[58:59], v[58:59], v[244:245]
	v_pk_add_f32 v[60:61], v[60:61], v[246:247]
	global_store_dwordx4 v252, v[58:61], s[44:45]
	s_add_u32 s44, s44, 0x10000
	s_addc_u32 s45, s45, 0
	s_waitcnt lgkmcnt(0)
	v_pk_add_f32 v[62:63], v[62:63], v[248:249]
	v_pk_add_f32 v[64:65], v[64:65], v[250:251]
	global_store_dwordx4 v252, v[62:65], s[44:45]
	s_add_i32 s21, s21, s72
	v_readlane_b32 s22, v209, 15
	s_add_i32 s20, s20, s22
	v_readlane_b32 s22, v209, 16
	s_add_i32 s8, s8, s22
	s_cmpk_lt_i32 s21, 0x400
	s_barrier
	s_cbranch_scc0 .LBB0_88
.LBB0_84:
	s_ashr_i32 s29, s21, 6
	s_lshr_b32 s22, s29, 29
	s_add_i32 s22, s29, s22
	s_ashr_i32 s30, s22, 3
	s_and_b32 s22, s22, 0x3ffff8
	s_sub_i32 s22, s29, s22
	s_lshl_b32 s24, s21, 7
	v_mov_b32_e32 v74, v131
	s_lshl_b32 s22, s22, 10
	s_and_b32 s24, s24, 0x380
	s_or_b32 s22, s22, s24
	s_load_dwordx2 s[24:25], s[12:13], 0x180
	v_lshrrev_b32_e32 v12, 4, v74
	v_ashrrev_i32_e32 v13, 3, v74
	s_waitcnt lgkmcnt(0)
	v_bfe_u32 v2, v74, 1, 3
	v_bitop3_b32 v14, v12, v2, 3 bitop3:0x6c
	v_add_u32_e32 v4, s22, v13
	s_waitcnt lgkmcnt(0)
	v_mov_b64_e32 v[2:3], s[24:25]
	s_movk_i32 s34, 0x2c80
	v_mad_i64_i32 v[4:5], s[24:25], v4, s34, v[2:3]
	s_lshl_b32 s24, s21, 4
	s_lshl_b32 s31, s30, 10
	s_and_b32 s24, s24, 0x380
	s_or_b32 s40, s31, s24
	s_load_dwordx2 s[24:25], s[12:13], 0x138
	v_xor_b32_e32 v0, v12, v74
	v_add_u32_e32 v8, s40, v13
	v_lshlrev_b32_e32 v0, 4, v0
	v_lshl_add_u32 v78, v74, 4, 16
	s_waitcnt lgkmcnt(0)
	v_mov_b64_e32 v[6:7], s[24:25]
	v_mad_i64_i32 v[8:9], s[24:25], v8, s34, v[6:7]
	v_and_b32_e32 v0, 0x70, v0
	v_add_u32_e32 v79, 0x8000, v78
	v_readfirstlane_b32 s24, v78
	v_lshl_add_u64 v[4:5], v[4:5], 0, v[0:1]
	s_mov_b32 m0, s24
	v_readfirstlane_b32 s24, v79
	v_add_u32_e32 v80, 0x1000, v78
	v_ashrrev_i32_e32 v10, 1, v74
	v_lshl_add_u64 v[8:9], v[8:9], 0, v[0:1]
	global_load_lds_dwordx4 v[4:5], off
	s_mov_b32 m0, s24
	s_mov_b64 s[42:43], 0x59000
	v_readfirstlane_b32 s24, v80
	v_add_u32_e32 v81, 0x9000, v78
	v_and_b32_e32 v77, 0xffffffc0, v10
	global_load_lds_dwordx4 v[8:9], off
	v_lshl_add_u64 v[10:11], v[4:5], 0, s[42:43]
	s_mov_b32 m0, s24
	v_readfirstlane_b32 s24, v81
	v_add_u32_e32 v82, 0x2000, v78
	global_load_lds_dwordx4 v[10:11], off
	v_lshl_add_u64 v[10:11], v[8:9], 0, s[42:43]
	s_mov_b32 m0, s24
	s_mov_b64 s[42:43], 0xb2000
	v_readfirstlane_b32 s24, v82
	v_add_u32_e32 v83, 0xa000, v78
	global_load_lds_dwordx4 v[10:11], off
	v_lshl_add_u64 v[10:11], v[4:5], 0, s[42:43]
	s_mov_b32 m0, s24
	v_readfirstlane_b32 s24, v83
	v_add_u32_e32 v84, 0x3000, v78
	global_load_lds_dwordx4 v[10:11], off
	v_lshl_add_u64 v[10:11], v[8:9], 0, s[42:43]
	s_mov_b32 m0, s24
	s_mov_b64 s[42:43], 0x10b000
	v_readfirstlane_b32 s24, v84
	v_add_u32_e32 v85, 0xb000, v78
	global_load_lds_dwordx4 v[10:11], off
	v_lshl_add_u64 v[4:5], v[4:5], 0, s[42:43]
	s_mov_b32 m0, s24
	v_readfirstlane_b32 s24, v85
	global_load_lds_dwordx4 v[4:5], off
	v_lshl_add_u64 v[4:5], v[8:9], 0, s[42:43]
	s_mov_b32 m0, s24
	v_and_b32_e32 v75, 15, v74
	global_load_lds_dwordx4 v[4:5], off
	v_lshlrev_b32_e32 v4, 7, v74
	v_or_b32_e32 v15, v77, v75
	v_and_b32_e32 v4, 0x2780, v4
	s_and_b32 s23, s20, 0x380
	v_lshl_add_u32 v0, v15, 7, 16
	v_add_u32_e32 v4, 16, v4
	v_lshlrev_b32_e32 v5, 4, v14
	s_lshl_b32 s24, s29, 10
	v_add_u32_e32 v86, v0, v5
	v_add_u32_e32 v87, v4, v5
	v_xor_b32_e32 v5, 64, v5
	s_or_b32 s23, s23, s24
	s_and_b32 s28, s8, 0x380
	s_waitcnt vmcnt(0)
	v_add_u32_e32 v89, v4, v5
	v_add_u32_e32 v4, s23, v13
	s_lshl_b32 s23, s30, 13
	s_waitcnt lgkmcnt(0)
	s_barrier
	v_subrev_u32_e32 v4, s23, v4
	s_or_b32 s23, s28, s31
	v_add_u32_e32 v88, v0, v5
	v_bitop3_b32 v0, v12, 7, v74 bitop3:0x48
	v_mad_i64_i32 v[66:67], s[24:25], v4, s34, v[2:3]
	v_add_u32_e32 v2, s23, v13
	v_mov_b32_e32 v34, 0
	v_bfe_u32 v76, v74, 4, 2
	v_lshlrev_b32_e32 v0, 4, v0
	v_mad_i64_i32 v[68:69], s[24:25], v2, s34, v[6:7]
	s_mov_b32 s23, 0
	v_mov_b32_e32 v35, v34
	v_mov_b32_e32 v36, v34
	v_mov_b32_e32 v37, v34
	v_mov_b32_e32 v6, v34
	v_mov_b32_e32 v7, v34
	v_mov_b32_e32 v8, v34
	v_mov_b32_e32 v9, v34
	v_mov_b32_e32 v42, v34
	v_mov_b32_e32 v43, v34
	v_mov_b32_e32 v44, v34
	v_mov_b32_e32 v45, v34
	v_mov_b32_e32 v10, v34
	v_mov_b32_e32 v11, v34
	v_mov_b32_e32 v12, v34
	v_mov_b32_e32 v13, v34
	v_mov_b32_e32 v38, v34
	v_mov_b32_e32 v39, v34
	v_mov_b32_e32 v40, v34
	v_mov_b32_e32 v41, v34
	v_mov_b32_e32 v14, v34
	v_mov_b32_e32 v15, v34
	v_mov_b32_e32 v16, v34
	v_mov_b32_e32 v17, v34
	v_mov_b32_e32 v46, v34
	v_mov_b32_e32 v47, v34
	v_mov_b32_e32 v48, v34
	v_mov_b32_e32 v49, v34
	v_mov_b32_e32 v22, v34
	v_mov_b32_e32 v23, v34
	v_mov_b32_e32 v24, v34
	v_mov_b32_e32 v25, v34
	v_mov_b32_e32 v50, v34
	v_mov_b32_e32 v51, v34
	v_mov_b32_e32 v52, v34
	v_mov_b32_e32 v53, v34
	v_mov_b32_e32 v18, v34
	v_mov_b32_e32 v19, v34
	v_mov_b32_e32 v20, v34
	v_mov_b32_e32 v21, v34
	v_mov_b32_e32 v54, v34
	v_mov_b32_e32 v55, v34
	v_mov_b32_e32 v56, v34
	v_mov_b32_e32 v57, v34
	v_mov_b32_e32 v30, v34
	v_mov_b32_e32 v31, v34
	v_mov_b32_e32 v32, v34
	v_mov_b32_e32 v33, v34
	v_mov_b32_e32 v58, v34
	v_mov_b32_e32 v59, v34
	v_mov_b32_e32 v60, v34
	v_mov_b32_e32 v61, v34
	v_mov_b32_e32 v26, v34
	v_mov_b32_e32 v27, v34
	v_mov_b32_e32 v28, v34
	v_mov_b32_e32 v29, v34
	v_mov_b32_e32 v62, v34
	v_mov_b32_e32 v63, v34
	v_mov_b32_e32 v64, v34
	v_mov_b32_e32 v65, v34
	v_mov_b32_e32 v2, v34
	v_mov_b32_e32 v3, v34
	v_mov_b32_e32 v4, v34
	v_mov_b32_e32 v5, v34
	s_load_dwordx2 s[44:45], s[12:13], 0x100
	v_lshrrev_b32_e32 v253, 5, v131
	v_and_b32_e32 v254, 31, v131
	v_lshlrev_b32_e32 v253, 13, v253
	v_lshl_or_b32 v252, v254, 4, v253
	s_lshl_b32 s46, s22, 13
	s_lshl_b32 s47, s40, 2
	s_add_i32 s46, s46, s47
	s_waitcnt lgkmcnt(0)
	s_add_u32 s44, s44, s46
	s_addc_u32 s45, s45, 0
	global_load_dwordx4 v[180:183], v252, s[44:45]
	s_add_u32 s44, s44, 0x10000
	s_addc_u32 s45, s45, 0
	global_load_dwordx4 v[184:187], v252, s[44:45]
	s_add_u32 s44, s44, 0x10000
	s_addc_u32 s45, s45, 0
	global_load_dwordx4 v[188:191], v252, s[44:45]
	s_add_u32 s44, s44, 0x10000
	s_addc_u32 s45, s45, 0
	global_load_dwordx4 v[196:199], v252, s[44:45]
	s_add_u32 s44, s44, 0x10000
	s_addc_u32 s45, s45, 0
	global_load_dwordx4 v[200:203], v252, s[44:45]
	s_add_u32 s44, s44, 0x10000
	s_addc_u32 s45, s45, 0
	global_load_dwordx4 v[204:207], v252, s[44:45]
	s_add_u32 s44, s44, 0x10000
	s_addc_u32 s45, s45, 0
	global_load_dwordx4 v[212:215], v252, s[44:45]
	s_add_u32 s44, s44, 0x10000
	s_addc_u32 s45, s45, 0
	global_load_dwordx4 v[216:219], v252, s[44:45]
	s_add_u32 s44, s44, 0x10000
	s_addc_u32 s45, s45, 0
	global_load_dwordx4 v[220:223], v252, s[44:45]
	s_add_u32 s44, s44, 0x10000
	s_addc_u32 s45, s45, 0
	global_load_dwordx4 v[224:227], v252, s[44:45]
	s_add_u32 s44, s44, 0x10000
	s_addc_u32 s45, s45, 0
	global_load_dwordx4 v[228:231], v252, s[44:45]
	s_add_u32 s44, s44, 0x10000
	s_addc_u32 s45, s45, 0
	global_load_dwordx4 v[232:235], v252, s[44:45]
	s_add_u32 s44, s44, 0x10000
	s_addc_u32 s45, s45, 0
	global_load_dwordx4 v[236:239], v252, s[44:45]
	s_add_u32 s44, s44, 0x10000
	s_addc_u32 s45, s45, 0
	global_load_dwordx4 v[240:243], v252, s[44:45]
	s_add_u32 s44, s44, 0x10000
	s_addc_u32 s45, s45, 0
	global_load_dwordx4 v[244:247], v252, s[44:45]
	s_add_u32 s44, s44, 0x10000
	s_addc_u32 s45, s45, 0
	global_load_dwordx4 v[248:251], v252, s[44:45]
	s_branch .LBB0_86

.LBB0_101:
	v_readlane_b32 s22, v209, 15
	s_add_i32 s20, s20, s22
	v_readlane_b32 s22, v209, 16
	s_add_i32 s21, s21, s72
	s_add_i32 s8, s8, s22
	s_cmpk_gt_i32 s21, 0x3ff
	s_waitcnt lgkmcnt(0)
	s_barrier
	s_cbranch_scc1 .LBB0_138
.LBB0_102:
	s_ashr_i32 s29, s21, 6
	s_lshr_b32 s22, s29, 29
	s_add_i32 s22, s29, s22
	s_ashr_i32 s30, s22, 3
	s_and_b32 s22, s22, 0x3ffff8
	s_sub_i32 s22, s29, s22
	s_lshl_b32 s24, s21, 7
	v_mov_b32_e32 v74, v131
	s_lshl_b32 s22, s22, 10
	s_and_b32 s24, s24, 0x380
	s_or_b32 s22, s22, s24
	s_load_dwordx2 s[24:25], s[12:13], 0x1b8
	v_lshrrev_b32_e32 v12, 4, v74
	v_ashrrev_i32_e32 v13, 3, v74
	s_waitcnt lgkmcnt(0)
	v_bfe_u32 v2, v74, 1, 3
	v_bitop3_b32 v14, v12, v2, 3 bitop3:0x6c
	v_add_u32_e32 v4, s22, v13
	s_waitcnt lgkmcnt(0)
	v_mov_b64_e32 v[2:3], s[24:25]
	v_mad_i64_i32 v[4:5], s[24:25], v4, s68, v[2:3]
	s_lshl_b32 s24, s21, 4
	s_lshl_b32 s31, s30, 10
	s_and_b32 s24, s24, 0x380
	s_or_b32 s40, s31, s24
	s_load_dwordx2 s[24:25], s[12:13], 0x128
	v_xor_b32_e32 v0, v12, v74
	v_add_u32_e32 v8, s40, v13
	v_lshlrev_b32_e32 v0, 4, v0
	v_lshl_add_u32 v78, v74, 4, 16
	s_waitcnt lgkmcnt(0)
	v_mov_b64_e32 v[6:7], s[24:25]
	v_mad_i64_i32 v[8:9], s[24:25], v8, s68, v[6:7]
	v_and_b32_e32 v0, 0x70, v0
	v_add_u32_e32 v79, 0x8000, v78
	v_readfirstlane_b32 s24, v78
	v_lshl_add_u64 v[4:5], v[4:5], 0, v[0:1]
	s_mov_b32 m0, s24
	v_readfirstlane_b32 s24, v79
	v_add_u32_e32 v80, 0x1000, v78
	v_ashrrev_i32_e32 v10, 1, v74
	v_lshl_add_u64 v[8:9], v[8:9], 0, v[0:1]
	global_load_lds_dwordx4 v[4:5], off
	s_mov_b32 m0, s24
	s_mov_b64 s[0:1], 0x9000
	v_readfirstlane_b32 s24, v80
	v_add_u32_e32 v81, 0x9000, v78
	v_and_b32_e32 v77, 0xffffffc0, v10
	global_load_lds_dwordx4 v[8:9], off
	v_lshl_add_u64 v[10:11], v[4:5], 0, s[0:1]
	s_mov_b32 m0, s24
	v_readfirstlane_b32 s24, v81
	v_add_u32_e32 v82, 0x2000, v78
	global_load_lds_dwordx4 v[10:11], off
	v_lshl_add_u64 v[10:11], v[8:9], 0, s[0:1]
	s_mov_b32 m0, s24
	s_mov_b64 s[0:1], 0x12000
	v_readfirstlane_b32 s24, v82
	v_add_u32_e32 v83, 0xa000, v78
	global_load_lds_dwordx4 v[10:11], off
	v_lshl_add_u64 v[10:11], v[4:5], 0, s[0:1]
	s_mov_b32 m0, s24
	v_readfirstlane_b32 s24, v83
	v_add_u32_e32 v84, 0x3000, v78
	global_load_lds_dwordx4 v[10:11], off
	v_lshl_add_u64 v[10:11], v[8:9], 0, s[0:1]
	s_mov_b32 m0, s24
	s_mov_b64 s[0:1], 0x1b000
	v_readfirstlane_b32 s24, v84
	v_add_u32_e32 v85, 0xb000, v78
	global_load_lds_dwordx4 v[10:11], off
	v_lshl_add_u64 v[4:5], v[4:5], 0, s[0:1]
	s_mov_b32 m0, s24
	v_readfirstlane_b32 s24, v85
	global_load_lds_dwordx4 v[4:5], off
	v_lshl_add_u64 v[4:5], v[8:9], 0, s[0:1]
	s_mov_b32 m0, s24
	v_and_b32_e32 v75, 15, v74
	global_load_lds_dwordx4 v[4:5], off
	v_lshlrev_b32_e32 v4, 7, v74
	v_or_b32_e32 v15, v77, v75
	v_and_b32_e32 v4, 0x2780, v4
	s_and_b32 s23, s20, 0x380
	v_lshl_add_u32 v0, v15, 7, 16
	v_add_u32_e32 v4, 16, v4
	v_lshlrev_b32_e32 v5, 4, v14
	s_lshl_b32 s24, s29, 10
	v_add_u32_e32 v86, v0, v5
	v_add_u32_e32 v87, v4, v5
	v_xor_b32_e32 v5, 64, v5
	s_or_b32 s23, s23, s24
	s_and_b32 s28, s8, 0x380
	s_waitcnt vmcnt(0)
	v_add_u32_e32 v89, v4, v5
	v_add_u32_e32 v4, s23, v13
	s_lshl_b32 s23, s30, 13
	s_waitcnt lgkmcnt(0)
	s_barrier
	v_subrev_u32_e32 v4, s23, v4
	s_or_b32 s23, s28, s31
	v_add_u32_e32 v88, v0, v5
	v_bitop3_b32 v0, v12, 7, v74 bitop3:0x48
	v_mad_i64_i32 v[66:67], s[24:25], v4, s68, v[2:3]
	v_add_u32_e32 v2, s23, v13
	v_mov_b32_e32 v34, 0
	v_bfe_u32 v76, v74, 4, 2
	v_lshlrev_b32_e32 v0, 4, v0
	v_mad_i64_i32 v[68:69], s[24:25], v2, s68, v[6:7]
	s_mov_b32 s23, 0
	v_mov_b32_e32 v35, v34
	v_mov_b32_e32 v36, v34
	v_mov_b32_e32 v37, v34
	v_mov_b32_e32 v6, v34
	v_mov_b32_e32 v7, v34
	v_mov_b32_e32 v8, v34
	v_mov_b32_e32 v9, v34
	v_mov_b32_e32 v42, v34
	v_mov_b32_e32 v43, v34
	v_mov_b32_e32 v44, v34
	v_mov_b32_e32 v45, v34
	v_mov_b32_e32 v10, v34
	v_mov_b32_e32 v11, v34
	v_mov_b32_e32 v12, v34
	v_mov_b32_e32 v13, v34
	v_mov_b32_e32 v38, v34
	v_mov_b32_e32 v39, v34
	v_mov_b32_e32 v40, v34
	v_mov_b32_e32 v41, v34
	v_mov_b32_e32 v14, v34
	v_mov_b32_e32 v15, v34
	v_mov_b32_e32 v16, v34
	v_mov_b32_e32 v17, v34
	v_mov_b32_e32 v46, v34
	v_mov_b32_e32 v47, v34
	v_mov_b32_e32 v48, v34
	v_mov_b32_e32 v49, v34
	v_mov_b32_e32 v22, v34
	v_mov_b32_e32 v23, v34
	v_mov_b32_e32 v24, v34
	v_mov_b32_e32 v25, v34
	v_mov_b32_e32 v50, v34
	v_mov_b32_e32 v51, v34
	v_mov_b32_e32 v52, v34
	v_mov_b32_e32 v53, v34
	v_mov_b32_e32 v18, v34
	v_mov_b32_e32 v19, v34
	v_mov_b32_e32 v20, v34
	v_mov_b32_e32 v21, v34
	v_mov_b32_e32 v54, v34
	v_mov_b32_e32 v55, v34
	v_mov_b32_e32 v56, v34
	v_mov_b32_e32 v57, v34
	v_mov_b32_e32 v30, v34
	v_mov_b32_e32 v31, v34
	v_mov_b32_e32 v32, v34
	v_mov_b32_e32 v33, v34
	v_mov_b32_e32 v58, v34
	v_mov_b32_e32 v59, v34
	v_mov_b32_e32 v60, v34
	v_mov_b32_e32 v61, v34
	v_mov_b32_e32 v26, v34
	v_mov_b32_e32 v27, v34
	v_mov_b32_e32 v28, v34
	v_mov_b32_e32 v29, v34
	v_mov_b32_e32 v62, v34
	v_mov_b32_e32 v63, v34
	v_mov_b32_e32 v64, v34
	v_mov_b32_e32 v65, v34
	v_mov_b32_e32 v2, v34
	v_mov_b32_e32 v3, v34
	v_mov_b32_e32 v4, v34
	v_mov_b32_e32 v5, v34
	s_load_dwordx2 s[44:45], s[12:13], 0x100
	v_lshrrev_b32_e32 v253, 5, v131
	v_and_b32_e32 v254, 31, v131
	v_lshlrev_b32_e32 v253, 13, v253
	v_lshl_or_b32 v252, v254, 4, v253
	s_lshl_b32 s46, s22, 13
	s_lshl_b32 s47, s40, 2
	s_add_i32 s46, s46, s47
	s_waitcnt lgkmcnt(0)
	s_add_u32 s44, s44, s46
	s_addc_u32 s45, s45, 0
	global_load_dwordx4 v[180:183], v252, s[44:45]
	s_add_u32 s44, s44, 0x10000
	s_addc_u32 s45, s45, 0
	global_load_dwordx4 v[184:187], v252, s[44:45]
	s_add_u32 s44, s44, 0x10000
	s_addc_u32 s45, s45, 0
	global_load_dwordx4 v[188:191], v252, s[44:45]
	s_add_u32 s44, s44, 0x10000
	s_addc_u32 s45, s45, 0
	global_load_dwordx4 v[196:199], v252, s[44:45]
	s_add_u32 s44, s44, 0x10000
	s_addc_u32 s45, s45, 0
	global_load_dwordx4 v[200:203], v252, s[44:45]
	s_add_u32 s44, s44, 0x10000
	s_addc_u32 s45, s45, 0
	global_load_dwordx4 v[204:207], v252, s[44:45]
	s_add_u32 s44, s44, 0x10000
	s_addc_u32 s45, s45, 0
	global_load_dwordx4 v[212:215], v252, s[44:45]
	s_add_u32 s44, s44, 0x10000
	s_addc_u32 s45, s45, 0
	global_load_dwordx4 v[216:219], v252, s[44:45]
	s_add_u32 s44, s44, 0x10000
	s_addc_u32 s45, s45, 0
	global_load_dwordx4 v[220:223], v252, s[44:45]
	s_add_u32 s44, s44, 0x10000
	s_addc_u32 s45, s45, 0
	global_load_dwordx4 v[224:227], v252, s[44:45]
	s_add_u32 s44, s44, 0x10000
	s_addc_u32 s45, s45, 0
	global_load_dwordx4 v[228:231], v252, s[44:45]
	s_add_u32 s44, s44, 0x10000
	s_addc_u32 s45, s45, 0
	global_load_dwordx4 v[232:235], v252, s[44:45]
	s_add_u32 s44, s44, 0x10000
	s_addc_u32 s45, s45, 0
	global_load_dwordx4 v[236:239], v252, s[44:45]
	s_add_u32 s44, s44, 0x10000
	s_addc_u32 s45, s45, 0
	global_load_dwordx4 v[240:243], v252, s[44:45]
	s_add_u32 s44, s44, 0x10000
	s_addc_u32 s45, s45, 0
	global_load_dwordx4 v[244:247], v252, s[44:45]
	s_add_u32 s44, s44, 0x10000
	s_addc_u32 s45, s45, 0
	global_load_dwordx4 v[248:251], v252, s[44:45]
	s_branch .LBB0_104

.LBB0_106:
	v_and_b32_e32 v0, 64, v74
	v_lshl_or_b32 v66, v76, 2, v77
	s_movk_i32 s23, 0x210
	v_lshl_add_u32 v0, v0, 2, 16
	v_lshlrev_b32_e32 v67, 2, v75
	v_mul_lo_u32 v66, v66, s23
	v_add3_u32 v0, v0, v67, v66
	ds_write2_b32 v0, v34, v6 offset1:16
	ds_write2_b32 v0, v35, v7 offset0:132 offset1:148
	v_add_u32_e32 v6, 0x400, v0
	ds_write2_b32 v6, v36, v8 offset0:8 offset1:24
	ds_write2_b32 v6, v37, v9 offset0:140 offset1:156
	ds_write2_b32 v0, v42, v10 offset0:32 offset1:48
	ds_write2_b32 v0, v43, v11 offset0:164 offset1:180
	ds_write2_b32 v6, v44, v12 offset0:40 offset1:56
	ds_write2_b32 v6, v45, v13 offset0:172 offset1:188
	v_add_u32_e32 v6, 0x2000, v0
	v_add_u32_e32 v7, 0x2400, v0
	ds_write2_b32 v6, v38, v14 offset0:64 offset1:80
	ds_write2_b32 v6, v39, v15 offset0:196 offset1:212
	ds_write2_b32 v7, v40, v16 offset0:72 offset1:88
	ds_write2_b32 v7, v41, v17 offset0:204 offset1:220
	ds_write2_b32 v6, v46, v22 offset0:96 offset1:112
	ds_write2_b32 v6, v47, v23 offset0:228 offset1:244
	ds_write2_b32 v7, v48, v24 offset0:104 offset1:120
	ds_write2_b32 v7, v49, v25 offset0:236 offset1:252
	v_add_u32_e32 v6, 0x4000, v0
	v_add_u32_e32 v7, 0x4400, v0
	v_add_u32_e32 v8, 0x4800, v0
	ds_write2_b32 v6, v50, v18 offset0:128 offset1:144
	ds_write2_b32 v7, v51, v19 offset0:4 offset1:20
	ds_write2_b32 v7, v52, v20 offset0:136 offset1:152
	ds_write2_b32 v8, v53, v21 offset0:12 offset1:28
	ds_write2_b32 v6, v54, v30 offset0:160 offset1:176
	ds_write2_b32 v7, v55, v31 offset0:36 offset1:52
	ds_write2_b32 v7, v56, v32 offset0:168 offset1:184
	ds_write2_b32 v8, v57, v33 offset0:44 offset1:60
	v_add_u32_e32 v6, 0x6000, v0
	v_add_u32_e32 v7, 0x6400, v0
	v_add_u32_e32 v0, 0x6800, v0
	ds_write2_b32 v6, v58, v26 offset0:192 offset1:208
	ds_write2_b32 v7, v59, v27 offset0:68 offset1:84
	ds_write2_b32 v7, v60, v28 offset0:200 offset1:216
	ds_write2_b32 v0, v61, v29 offset0:76 offset1:92
	ds_write2_b32 v6, v62, v2 offset0:224 offset1:240
	ds_write2_b32 v7, v63, v3 offset0:100 offset1:116
	ds_write2_b32 v7, v64, v4 offset0:232 offset1:248
	ds_write2_b32 v0, v65, v5 offset0:108 offset1:124
	s_load_dwordx2 s[44:45], s[12:13], 0x100
	s_load_dwordx2 s[46:47], s[12:13], 0x160
	s_load_dwordx2 s[48:49], s[12:13], 0x1d0
	s_waitcnt vmcnt(0) lgkmcnt(0)
	s_barrier
	s_lshl_b32 s24, s22, 13
	s_lshl_b32 s25, s40, 2
	s_add_i32 s24, s24, s25
	s_add_u32 s44, s44, s24
	s_addc_u32 s45, s45, 0
	s_mul_i32 s24, s22, s81
	s_lshl_b32 s25, s40, 1
	s_add_i32 s24, s24, s25
	s_add_u32 s46, s46, s24
	s_addc_u32 s47, s47, 0
	s_lshl_b32 s24, s22, 2
	s_add_u32 s48, s48, s24
	s_addc_u32 s49, s49, 0
	v_lshrrev_b32_e32 v66, 5, v131
	v_and_b32_e32 v67, 31, v131
	s_movk_i32 s25, 0x210
	v_lshlrev_b32_e32 v68, 4, v67
	v_mad_u32_u24 v69, v66, s25, v68
	v_add_u32_e32 v69, 16, v69
	ds_read_b128 v[2:5], v69
	ds_read_b128 v[6:9], v69 offset:4224
	ds_read_b128 v[10:13], v69 offset:8448
	ds_read_b128 v[14:17], v69 offset:12672
	ds_read_b128 v[18:21], v69 offset:16896
	ds_read_b128 v[22:25], v69 offset:21120
	ds_read_b128 v[26:29], v69 offset:25344
	ds_read_b128 v[30:33], v69 offset:29568
	ds_read_b128 v[34:37], v69 offset:33792
	ds_read_b128 v[38:41], v69 offset:38016
	ds_read_b128 v[42:45], v69 offset:42240
	ds_read_b128 v[46:49], v69 offset:46464
	ds_read_b128 v[50:53], v69 offset:50688
	ds_read_b128 v[54:57], v69 offset:54912
	ds_read_b128 v[58:61], v69 offset:59136
	ds_read_b128 v[62:65], v69 offset:63360
	v_lshlrev_b32_e32 v70, 3, v67
	v_mad_u32_u24 v70, v66, s81, v70
	v_lshlrev_b32_e32 v71, 2, v66
	s_waitcnt lgkmcnt(15)
	v_pk_add_f32 v[2:3], v[2:3], v[180:181]
	v_pk_add_f32 v[4:5], v[4:5], v[182:183]
	global_store_dwordx4 v252, v[2:5], s[44:45]
	v_cvt_pk_bf16_f32 v180, v2, v3
	v_cvt_pk_bf16_f32 v181, v4, v5
	global_store_dwordx2 v70, v[180:181], s[46:47]
	v_mul_f32_e32 v182, v2, v2
	v_fmac_f32_e32 v182, v3, v3
	v_fmac_f32_e32 v182, v4, v4
	v_fmac_f32_e32 v182, v5, v5
	s_add_u32 s44, s44, 0x10000
	s_addc_u32 s45, s45, 0
	s_add_u32 s46, s46, 0x8400
	s_addc_u32 s47, s47, 0
	s_waitcnt lgkmcnt(14)
	v_pk_add_f32 v[6:7], v[6:7], v[184:185]
	v_pk_add_f32 v[8:9], v[8:9], v[186:187]
	global_store_dwordx4 v252, v[6:9], s[44:45]
	v_cvt_pk_bf16_f32 v184, v6, v7
	v_cvt_pk_bf16_f32 v185, v8, v9
	global_store_dwordx2 v70, v[184:185], s[46:47]
	v_mul_f32_e32 v186, v6, v6
	v_fmac_f32_e32 v186, v7, v7
	v_fmac_f32_e32 v186, v8, v8
	v_fmac_f32_e32 v186, v9, v9
	s_add_u32 s44, s44, 0x10000
	s_addc_u32 s45, s45, 0
	s_add_u32 s46, s46, 0x8400
	s_addc_u32 s47, s47, 0
	s_waitcnt lgkmcnt(13)
	v_pk_add_f32 v[10:11], v[10:11], v[188:189]
	v_pk_add_f32 v[12:13], v[12:13], v[190:191]
	global_store_dwordx4 v252, v[10:13], s[44:45]
	v_cvt_pk_bf16_f32 v188, v10, v11
	v_cvt_pk_bf16_f32 v189, v12, v13
	global_store_dwordx2 v70, v[188:189], s[46:47]
	v_mul_f32_e32 v190, v10, v10
	v_fmac_f32_e32 v190, v11, v11
	v_fmac_f32_e32 v190, v12, v12
	v_fmac_f32_e32 v190, v13, v13
	s_add_u32 s44, s44, 0x10000
	s_addc_u32 s45, s45, 0
	s_add_u32 s46, s46, 0x8400
	s_addc_u32 s47, s47, 0
	s_waitcnt lgkmcnt(12)
	v_pk_add_f32 v[14:15], v[14:15], v[196:197]
	v_pk_add_f32 v[16:17], v[16:17], v[198:199]
	global_store_dwordx4 v252, v[14:17], s[44:45]
	v_cvt_pk_bf16_f32 v196, v14, v15
	v_cvt_pk_bf16_f32 v197, v16, v17
	global_store_dwordx2 v70, v[196:197], s[46:47]
	v_mul_f32_e32 v198, v14, v14
	v_fmac_f32_e32 v198, v15, v15
	v_fmac_f32_e32 v198, v16, v16
	v_fmac_f32_e32 v198, v17, v17
	s_add_u32 s44, s44, 0x10000
	s_addc_u32 s45, s45, 0
	s_add_u32 s46, s46, 0x8400
	s_addc_u32 s47, s47, 0
	s_waitcnt lgkmcnt(11)
	v_pk_add_f32 v[18:19], v[18:19], v[200:201]
	v_pk_add_f32 v[20:21], v[20:21], v[202:203]
	global_store_dwordx4 v252, v[18:21], s[44:45]
	v_cvt_pk_bf16_f32 v200, v18, v19
	v_cvt_pk_bf16_f32 v201, v20, v21
	global_store_dwordx2 v70, v[200:201], s[46:47]
	v_mul_f32_e32 v202, v18, v18
	v_fmac_f32_e32 v202, v19, v19
	v_fmac_f32_e32 v202, v20, v20
	v_fmac_f32_e32 v202, v21, v21
	s_add_u32 s44, s44, 0x10000
	s_addc_u32 s45, s45, 0
	s_add_u32 s46, s46, 0x8400
	s_addc_u32 s47, s47, 0
	s_waitcnt lgkmcnt(10)
	v_pk_add_f32 v[22:23], v[22:23], v[204:205]
	v_pk_add_f32 v[24:25], v[24:25], v[206:207]
	global_store_dwordx4 v252, v[22:25], s[44:45]
	v_cvt_pk_bf16_f32 v204, v22, v23
	v_cvt_pk_bf16_f32 v205, v24, v25
	global_store_dwordx2 v70, v[204:205], s[46:47]
	v_mul_f32_e32 v206, v22, v22
	v_fmac_f32_e32 v206, v23, v23
	v_fmac_f32_e32 v206, v24, v24
	v_fmac_f32_e32 v206, v25, v25
	s_add_u32 s44, s44, 0x10000
	s_addc_u32 s45, s45, 0
	s_add_u32 s46, s46, 0x8400
	s_addc_u32 s47, s47, 0
	s_waitcnt lgkmcnt(9)
	v_pk_add_f32 v[26:27], v[26:27], v[212:213]
	v_pk_add_f32 v[28:29], v[28:29], v[214:215]
	global_store_dwordx4 v252, v[26:29], s[44:45]
	v_cvt_pk_bf16_f32 v212, v26, v27
	v_cvt_pk_bf16_f32 v213, v28, v29
	global_store_dwordx2 v70, v[212:213], s[46:47]
	v_mul_f32_e32 v214, v26, v26
	v_fmac_f32_e32 v214, v27, v27
	v_fmac_f32_e32 v214, v28, v28
	v_fmac_f32_e32 v214, v29, v29
	s_add_u32 s44, s44, 0x10000
	s_addc_u32 s45, s45, 0
	s_add_u32 s46, s46, 0x8400
	s_addc_u32 s47, s47, 0
	s_waitcnt lgkmcnt(8)
	v_pk_add_f32 v[30:31], v[30:31], v[216:217]
	v_pk_add_f32 v[32:33], v[32:33], v[218:219]
	global_store_dwordx4 v252, v[30:33], s[44:45]
	v_cvt_pk_bf16_f32 v216, v30, v31
	v_cvt_pk_bf16_f32 v217, v32, v33
	global_store_dwordx2 v70, v[216:217], s[46:47]
	v_mul_f32_e32 v218, v30, v30
	v_fmac_f32_e32 v218, v31, v31
	v_fmac_f32_e32 v218, v32, v32
	v_fmac_f32_e32 v218, v33, v33
	s_add_u32 s44, s44, 0x10000
	s_addc_u32 s45, s45, 0
	s_add_u32 s46, s46, 0x8400
	s_addc_u32 s47, s47, 0
	s_waitcnt lgkmcnt(7)
	v_pk_add_f32 v[34:35], v[34:35], v[220:221]
	v_pk_add_f32 v[36:37], v[36:37], v[222:223]
	global_store_dwordx4 v252, v[34:37], s[44:45]
	v_cvt_pk_bf16_f32 v220, v34, v35
	v_cvt_pk_bf16_f32 v221, v36, v37
	global_store_dwordx2 v70, v[220:221], s[46:47]
	v_mul_f32_e32 v222, v34, v34
	v_fmac_f32_e32 v222, v35, v35
	v_fmac_f32_e32 v222, v36, v36
	v_fmac_f32_e32 v222, v37, v37
	s_add_u32 s44, s44, 0x10000
	s_addc_u32 s45, s45, 0
	s_add_u32 s46, s46, 0x8400
	s_addc_u32 s47, s47, 0
	s_waitcnt lgkmcnt(6)
	v_pk_add_f32 v[38:39], v[38:39], v[224:225]
	v_pk_add_f32 v[40:41], v[40:41], v[226:227]
	global_store_dwordx4 v252, v[38:41], s[44:45]
	v_cvt_pk_bf16_f32 v224, v38, v39
	v_cvt_pk_bf16_f32 v225, v40, v41
	global_store_dwordx2 v70, v[224:225], s[46:47]
	v_mul_f32_e32 v226, v38, v38
	v_fmac_f32_e32 v226, v39, v39
	v_fmac_f32_e32 v226, v40, v40
	v_fmac_f32_e32 v226, v41, v41
	s_add_u32 s44, s44, 0x10000
	s_addc_u32 s45, s45, 0
	s_add_u32 s46, s46, 0x8400
	s_addc_u32 s47, s47, 0
	s_waitcnt lgkmcnt(5)
	v_pk_add_f32 v[42:43], v[42:43], v[228:229]
	v_pk_add_f32 v[44:45], v[44:45], v[230:231]
	global_store_dwordx4 v252, v[42:45], s[44:45]
	v_cvt_pk_bf16_f32 v228, v42, v43
	v_cvt_pk_bf16_f32 v229, v44, v45
	global_store_dwordx2 v70, v[228:229], s[46:47]
	v_mul_f32_e32 v230, v42, v42
	v_fmac_f32_e32 v230, v43, v43
	v_fmac_f32_e32 v230, v44, v44
	v_fmac_f32_e32 v230, v45, v45
	s_add_u32 s44, s44, 0x10000
	s_addc_u32 s45, s45, 0
	s_add_u32 s46, s46, 0x8400
	s_addc_u32 s47, s47, 0
	s_waitcnt lgkmcnt(4)
	v_pk_add_f32 v[46:47], v[46:47], v[232:233]
	v_pk_add_f32 v[48:49], v[48:49], v[234:235]
	global_store_dwordx4 v252, v[46:49], s[44:45]
	v_cvt_pk_bf16_f32 v232, v46, v47
	v_cvt_pk_bf16_f32 v233, v48, v49
	global_store_dwordx2 v70, v[232:233], s[46:47]
	v_mul_f32_e32 v234, v46, v46
	v_fmac_f32_e32 v234, v47, v47
	v_fmac_f32_e32 v234, v48, v48
	v_fmac_f32_e32 v234, v49, v49
	s_add_u32 s44, s44, 0x10000
	s_addc_u32 s45, s45, 0
	s_add_u32 s46, s46, 0x8400
	s_addc_u32 s47, s47, 0
	s_waitcnt lgkmcnt(3)
	v_pk_add_f32 v[50:51], v[50:51], v[236:237]
	v_pk_add_f32 v[52:53], v[52:53], v[238:239]
	global_store_dwordx4 v252, v[50:53], s[44:45]
	v_cvt_pk_bf16_f32 v236, v50, v51
	v_cvt_pk_bf16_f32 v237, v52, v53
	global_store_dwordx2 v70, v[236:237], s[46:47]
	v_mul_f32_e32 v238, v50, v50
	v_fmac_f32_e32 v238, v51, v51
	v_fmac_f32_e32 v238, v52, v52
	v_fmac_f32_e32 v238, v53, v53
	s_add_u32 s44, s44, 0x10000
	s_addc_u32 s45, s45, 0
	s_add_u32 s46, s46, 0x8400
	s_addc_u32 s47, s47, 0
	s_waitcnt lgkmcnt(2)
	v_pk_add_f32 v[54:55], v[54:55], v[240:241]
	v_pk_add_f32 v[56:57], v[56:57], v[242:243]
	global_store_dwordx4 v252, v[54:57], s[44:45]
	v_cvt_pk_bf16_f32 v240, v54, v55
	v_cvt_pk_bf16_f32 v241, v56, v57
	global_store_dwordx2 v70, v[240:241], s[46:47]
	v_mul_f32_e32 v242, v54, v54
	v_fmac_f32_e32 v242, v55, v55
	v_fmac_f32_e32 v242, v56, v56
	v_fmac_f32_e32 v242, v57, v57
	s_add_u32 s44, s44, 0x10000
	s_addc_u32 s45, s45, 0
	s_add_u32 s46, s46, 0x8400
	s_addc_u32 s47, s47, 0
	s_waitcnt lgkmcnt(1)
	v_pk_add_f32 v[58:59], v[58:59], v[244:245]
	v_pk_add_f32 v[60:61], v[60:61], v[246:247]
	global_store_dwordx4 v252, v[58:61], s[44:45]
	v_cvt_pk_bf16_f32 v244, v58, v59
	v_cvt_pk_bf16_f32 v245, v60, v61
	global_store_dwordx2 v70, v[244:245], s[46:47]
	v_mul_f32_e32 v246, v58, v58
	v_fmac_f32_e32 v246, v59, v59
	v_fmac_f32_e32 v246, v60, v60
	v_fmac_f32_e32 v246, v61, v61
	s_add_u32 s44, s44, 0x10000
	s_addc_u32 s45, s45, 0
	s_add_u32 s46, s46, 0x8400
	s_addc_u32 s47, s47, 0
	s_waitcnt lgkmcnt(0)
	v_pk_add_f32 v[62:63], v[62:63], v[248:249]
	v_pk_add_f32 v[64:65], v[64:65], v[250:251]
	global_store_dwordx4 v252, v[62:65], s[44:45]
	v_cvt_pk_bf16_f32 v248, v62, v63
	v_cvt_pk_bf16_f32 v249, v64, v65
	global_store_dwordx2 v70, v[248:249], s[46:47]
	v_mul_f32_e32 v250, v62, v62
	v_fmac_f32_e32 v250, v63, v63
	v_fmac_f32_e32 v250, v64, v64
	v_fmac_f32_e32 v250, v65, v65
	s_nop 1
	v_add_f32_dpp v182, v182, v182 quad_perm:[1,0,3,2] row_mask:0xf bank_mask:0xf
	v_add_f32_dpp v186, v186, v186 quad_perm:[1,0,3,2] row_mask:0xf bank_mask:0xf
	v_add_f32_dpp v190, v190, v190 quad_perm:[1,0,3,2] row_mask:0xf bank_mask:0xf
	v_add_f32_dpp v198, v198, v198 quad_perm:[1,0,3,2] row_mask:0xf bank_mask:0xf
	v_add_f32_dpp v202, v202, v202 quad_perm:[1,0,3,2] row_mask:0xf bank_mask:0xf
	v_add_f32_dpp v206, v206, v206 quad_perm:[1,0,3,2] row_mask:0xf bank_mask:0xf
	v_add_f32_dpp v214, v214, v214 quad_perm:[1,0,3,2] row_mask:0xf bank_mask:0xf
	v_add_f32_dpp v218, v218, v218 quad_perm:[1,0,3,2] row_mask:0xf bank_mask:0xf
	v_add_f32_dpp v222, v222, v222 quad_perm:[1,0,3,2] row_mask:0xf bank_mask:0xf
	v_add_f32_dpp v226, v226, v226 quad_perm:[1,0,3,2] row_mask:0xf bank_mask:0xf
	v_add_f32_dpp v230, v230, v230 quad_perm:[1,0,3,2] row_mask:0xf bank_mask:0xf
	v_add_f32_dpp v234, v234, v234 quad_perm:[1,0,3,2] row_mask:0xf bank_mask:0xf
	v_add_f32_dpp v238, v238, v238 quad_perm:[1,0,3,2] row_mask:0xf bank_mask:0xf
	v_add_f32_dpp v242, v242, v242 quad_perm:[1,0,3,2] row_mask:0xf bank_mask:0xf
	v_add_f32_dpp v246, v246, v246 quad_perm:[1,0,3,2] row_mask:0xf bank_mask:0xf
	v_add_f32_dpp v250, v250, v250 quad_perm:[1,0,3,2] row_mask:0xf bank_mask:0xf
	v_add_f32_dpp v182, v182, v182 quad_perm:[2,3,0,1] row_mask:0xf bank_mask:0xf
	v_add_f32_dpp v186, v186, v186 quad_perm:[2,3,0,1] row_mask:0xf bank_mask:0xf
	v_add_f32_dpp v190, v190, v190 quad_perm:[2,3,0,1] row_mask:0xf bank_mask:0xf
	v_add_f32_dpp v198, v198, v198 quad_perm:[2,3,0,1] row_mask:0xf bank_mask:0xf
	v_add_f32_dpp v202, v202, v202 quad_perm:[2,3,0,1] row_mask:0xf bank_mask:0xf
	v_add_f32_dpp v206, v206, v206 quad_perm:[2,3,0,1] row_mask:0xf bank_mask:0xf
	v_add_f32_dpp v214, v214, v214 quad_perm:[2,3,0,1] row_mask:0xf bank_mask:0xf
	v_add_f32_dpp v218, v218, v218 quad_perm:[2,3,0,1] row_mask:0xf bank_mask:0xf
	v_add_f32_dpp v222, v222, v222 quad_perm:[2,3,0,1] row_mask:0xf bank_mask:0xf
	v_add_f32_dpp v226, v226, v226 quad_perm:[2,3,0,1] row_mask:0xf bank_mask:0xf
	v_add_f32_dpp v230, v230, v230 quad_perm:[2,3,0,1] row_mask:0xf bank_mask:0xf
	v_add_f32_dpp v234, v234, v234 quad_perm:[2,3,0,1] row_mask:0xf bank_mask:0xf
	v_add_f32_dpp v238, v238, v238 quad_perm:[2,3,0,1] row_mask:0xf bank_mask:0xf
	v_add_f32_dpp v242, v242, v242 quad_perm:[2,3,0,1] row_mask:0xf bank_mask:0xf
	v_add_f32_dpp v246, v246, v246 quad_perm:[2,3,0,1] row_mask:0xf bank_mask:0xf
	v_add_f32_dpp v250, v250, v250 quad_perm:[2,3,0,1] row_mask:0xf bank_mask:0xf
	v_add_f32_dpp v182, v182, v182 row_half_mirror row_mask:0xf bank_mask:0xf
	v_add_f32_dpp v186, v186, v186 row_half_mirror row_mask:0xf bank_mask:0xf
	v_add_f32_dpp v190, v190, v190 row_half_mirror row_mask:0xf bank_mask:0xf
	v_add_f32_dpp v198, v198, v198 row_half_mirror row_mask:0xf bank_mask:0xf
	v_add_f32_dpp v202, v202, v202 row_half_mirror row_mask:0xf bank_mask:0xf
	v_add_f32_dpp v206, v206, v206 row_half_mirror row_mask:0xf bank_mask:0xf
	v_add_f32_dpp v214, v214, v214 row_half_mirror row_mask:0xf bank_mask:0xf
	v_add_f32_dpp v218, v218, v218 row_half_mirror row_mask:0xf bank_mask:0xf
	v_add_f32_dpp v222, v222, v222 row_half_mirror row_mask:0xf bank_mask:0xf
	v_add_f32_dpp v226, v226, v226 row_half_mirror row_mask:0xf bank_mask:0xf
	v_add_f32_dpp v230, v230, v230 row_half_mirror row_mask:0xf bank_mask:0xf
	v_add_f32_dpp v234, v234, v234 row_half_mirror row_mask:0xf bank_mask:0xf
	v_add_f32_dpp v238, v238, v238 row_half_mirror row_mask:0xf bank_mask:0xf
	v_add_f32_dpp v242, v242, v242 row_half_mirror row_mask:0xf bank_mask:0xf
	v_add_f32_dpp v246, v246, v246 row_half_mirror row_mask:0xf bank_mask:0xf
	v_add_f32_dpp v250, v250, v250 row_half_mirror row_mask:0xf bank_mask:0xf
	v_add_f32_dpp v182, v182, v182 row_mirror row_mask:0xf bank_mask:0xf
	v_add_f32_dpp v186, v186, v186 row_mirror row_mask:0xf bank_mask:0xf
	v_add_f32_dpp v190, v190, v190 row_mirror row_mask:0xf bank_mask:0xf
	v_add_f32_dpp v198, v198, v198 row_mirror row_mask:0xf bank_mask:0xf
	v_add_f32_dpp v202, v202, v202 row_mirror row_mask:0xf bank_mask:0xf
	v_add_f32_dpp v206, v206, v206 row_mirror row_mask:0xf bank_mask:0xf
	v_add_f32_dpp v214, v214, v214 row_mirror row_mask:0xf bank_mask:0xf
	v_add_f32_dpp v218, v218, v218 row_mirror row_mask:0xf bank_mask:0xf
	v_add_f32_dpp v222, v222, v222 row_mirror row_mask:0xf bank_mask:0xf
	v_add_f32_dpp v226, v226, v226 row_mirror row_mask:0xf bank_mask:0xf
	v_add_f32_dpp v230, v230, v230 row_mirror row_mask:0xf bank_mask:0xf
	v_add_f32_dpp v234, v234, v234 row_mirror row_mask:0xf bank_mask:0xf
	v_add_f32_dpp v238, v238, v238 row_mirror row_mask:0xf bank_mask:0xf
	v_add_f32_dpp v242, v242, v242 row_mirror row_mask:0xf bank_mask:0xf
	v_add_f32_dpp v246, v246, v246 row_mirror row_mask:0xf bank_mask:0xf
	v_add_f32_dpp v250, v250, v250 row_mirror row_mask:0xf bank_mask:0xf
	v_add_f32_dpp v182, v182, v182 row_bcast:15 row_mask:0xa bank_mask:0xf
	v_add_f32_dpp v186, v186, v186 row_bcast:15 row_mask:0xa bank_mask:0xf
	v_add_f32_dpp v190, v190, v190 row_bcast:15 row_mask:0xa bank_mask:0xf
	v_add_f32_dpp v198, v198, v198 row_bcast:15 row_mask:0xa bank_mask:0xf
	v_add_f32_dpp v202, v202, v202 row_bcast:15 row_mask:0xa bank_mask:0xf
	v_add_f32_dpp v206, v206, v206 row_bcast:15 row_mask:0xa bank_mask:0xf
	v_add_f32_dpp v214, v214, v214 row_bcast:15 row_mask:0xa bank_mask:0xf
	v_add_f32_dpp v218, v218, v218 row_bcast:15 row_mask:0xa bank_mask:0xf
	v_add_f32_dpp v222, v222, v222 row_bcast:15 row_mask:0xa bank_mask:0xf
	v_add_f32_dpp v226, v226, v226 row_bcast:15 row_mask:0xa bank_mask:0xf
	v_add_f32_dpp v230, v230, v230 row_bcast:15 row_mask:0xa bank_mask:0xf
	v_add_f32_dpp v234, v234, v234 row_bcast:15 row_mask:0xa bank_mask:0xf
	v_add_f32_dpp v238, v238, v238 row_bcast:15 row_mask:0xa bank_mask:0xf
	v_add_f32_dpp v242, v242, v242 row_bcast:15 row_mask:0xa bank_mask:0xf
	v_add_f32_dpp v246, v246, v246 row_bcast:15 row_mask:0xa bank_mask:0xf
	v_add_f32_dpp v250, v250, v250 row_bcast:15 row_mask:0xa bank_mask:0xf
	s_mov_b32 exec_lo, 0x10000
	s_mov_b32 exec_hi, 0x10000
	global_atomic_add_f32 v71, v182, s[48:49]
	global_atomic_add_f32 v71, v186, s[48:49] offset:32
	global_atomic_add_f32 v71, v190, s[48:49] offset:64
	global_atomic_add_f32 v71, v198, s[48:49] offset:96
	global_atomic_add_f32 v71, v202, s[48:49] offset:128
	global_atomic_add_f32 v71, v206, s[48:49] offset:160
	global_atomic_add_f32 v71, v214, s[48:49] offset:192
	global_atomic_add_f32 v71, v218, s[48:49] offset:224
	global_atomic_add_f32 v71, v222, s[48:49] offset:256
	global_atomic_add_f32 v71, v226, s[48:49] offset:288
	global_atomic_add_f32 v71, v230, s[48:49] offset:320
	global_atomic_add_f32 v71, v234, s[48:49] offset:352
	global_atomic_add_f32 v71, v238, s[48:49] offset:384
	global_atomic_add_f32 v71, v242, s[48:49] offset:416
	global_atomic_add_f32 v71, v246, s[48:49] offset:448
	global_atomic_add_f32 v71, v250, s[48:49] offset:480
	s_mov_b64 exec, -1
	s_branch .LBB0_101

.LBB0_189:
	s_ashr_i32 s29, s21, 6
	s_lshr_b32 s22, s29, 29
	s_add_i32 s22, s29, s22
	s_ashr_i32 s30, s22, 3
	s_and_b32 s22, s22, 0x3ffff8
	s_sub_i32 s22, s29, s22
	s_lshl_b32 s24, s21, 7
	v_mov_b32_e32 v74, v131
	s_lshl_b32 s22, s22, 10
	s_and_b32 s24, s24, 0x380
	s_or_b32 s22, s22, s24
	s_load_dwordx2 s[24:25], s[12:13], 0x178
	v_lshrrev_b32_e32 v12, 4, v74
	v_ashrrev_i32_e32 v13, 3, v74
	s_waitcnt lgkmcnt(0)
	v_bfe_u32 v2, v74, 1, 3
	v_bitop3_b32 v14, v12, v2, 3 bitop3:0x6c
	v_add_u32_e32 v4, s22, v13
	s_waitcnt lgkmcnt(0)
	v_mov_b64_e32 v[2:3], s[24:25]
	v_mad_i64_i32 v[4:5], s[24:25], v4, s81, v[2:3]
	s_lshl_b32 s24, s21, 4
	s_lshl_b32 s31, s30, 10
	s_and_b32 s24, s24, 0x380
	s_or_b32 s42, s31, s24
	s_load_dwordx2 s[24:25], s[12:13], 0x118
	v_xor_b32_e32 v0, v12, v74
	v_add_u32_e32 v8, s42, v13
	v_lshlrev_b32_e32 v0, 4, v0
	v_lshl_add_u32 v78, v74, 4, 16
	s_waitcnt lgkmcnt(0)
	v_mov_b64_e32 v[6:7], s[24:25]
	v_mad_i64_i32 v[8:9], s[24:25], v8, s81, v[6:7]
	v_and_b32_e32 v0, 0x70, v0
	v_add_u32_e32 v79, 0x8000, v78
	v_readfirstlane_b32 s24, v78
	v_lshl_add_u64 v[4:5], v[4:5], 0, v[0:1]
	s_mov_b32 m0, s24
	v_readfirstlane_b32 s24, v79
	v_add_u32_e32 v80, 0x1000, v78
	v_ashrrev_i32_e32 v10, 1, v74
	v_lshl_add_u64 v[8:9], v[8:9], 0, v[0:1]
	global_load_lds_dwordx4 v[4:5], off
	s_mov_b32 m0, s24
	s_mov_b64 s[40:41], 0x21000
	v_readfirstlane_b32 s24, v80
	v_add_u32_e32 v81, 0x9000, v78
	v_and_b32_e32 v77, 0xffffffc0, v10
	global_load_lds_dwordx4 v[8:9], off
	v_lshl_add_u64 v[10:11], v[4:5], 0, s[40:41]
	s_mov_b32 m0, s24
	v_readfirstlane_b32 s24, v81
	v_add_u32_e32 v82, 0x2000, v78
	global_load_lds_dwordx4 v[10:11], off
	v_lshl_add_u64 v[10:11], v[8:9], 0, s[40:41]
	s_mov_b32 m0, s24
	s_mov_b64 s[40:41], 0x42000
	v_readfirstlane_b32 s24, v82
	v_add_u32_e32 v83, 0xa000, v78
	global_load_lds_dwordx4 v[10:11], off
	v_lshl_add_u64 v[10:11], v[4:5], 0, s[40:41]
	s_mov_b32 m0, s24
	v_readfirstlane_b32 s24, v83
	v_add_u32_e32 v84, 0x3000, v78
	global_load_lds_dwordx4 v[10:11], off
	v_lshl_add_u64 v[10:11], v[8:9], 0, s[40:41]
	s_mov_b32 m0, s24
	s_mov_b64 s[40:41], 0x63000
	v_readfirstlane_b32 s24, v84
	v_add_u32_e32 v85, 0xb000, v78
	global_load_lds_dwordx4 v[10:11], off
	v_lshl_add_u64 v[4:5], v[4:5], 0, s[40:41]
	s_mov_b32 m0, s24
	v_readfirstlane_b32 s24, v85
	global_load_lds_dwordx4 v[4:5], off
	v_lshl_add_u64 v[4:5], v[8:9], 0, s[40:41]
	s_mov_b32 m0, s24
	v_and_b32_e32 v75, 15, v74
	global_load_lds_dwordx4 v[4:5], off
	v_lshlrev_b32_e32 v4, 7, v74
	v_or_b32_e32 v15, v77, v75
	v_and_b32_e32 v4, 0x2780, v4
	s_and_b32 s23, s20, 0x380
	v_lshl_add_u32 v0, v15, 7, 16
	v_add_u32_e32 v4, 16, v4
	v_lshlrev_b32_e32 v5, 4, v14
	s_lshl_b32 s24, s29, 10
	v_add_u32_e32 v86, v0, v5
	v_add_u32_e32 v87, v4, v5
	v_xor_b32_e32 v5, 64, v5
	s_or_b32 s23, s23, s24
	s_and_b32 s28, s8, 0x380
	s_waitcnt vmcnt(0)
	v_add_u32_e32 v89, v4, v5
	v_add_u32_e32 v4, s23, v13
	s_lshl_b32 s23, s30, 13
	s_waitcnt lgkmcnt(0)
	s_barrier
	v_subrev_u32_e32 v4, s23, v4
	s_or_b32 s23, s28, s31
	v_add_u32_e32 v88, v0, v5
	v_bitop3_b32 v0, v12, 7, v74 bitop3:0x48
	v_mad_i64_i32 v[66:67], s[24:25], v4, s81, v[2:3]
	v_add_u32_e32 v2, s23, v13
	v_mov_b32_e32 v34, 0
	v_bfe_u32 v76, v74, 4, 2
	v_lshlrev_b32_e32 v0, 4, v0
	v_mad_i64_i32 v[68:69], s[24:25], v2, s81, v[6:7]
	s_mov_b32 s23, 0
	v_mov_b32_e32 v35, v34
	v_mov_b32_e32 v36, v34
	v_mov_b32_e32 v37, v34
	v_mov_b32_e32 v6, v34
	v_mov_b32_e32 v7, v34
	v_mov_b32_e32 v8, v34
	v_mov_b32_e32 v9, v34
	v_mov_b32_e32 v42, v34
	v_mov_b32_e32 v43, v34
	v_mov_b32_e32 v44, v34
	v_mov_b32_e32 v45, v34
	v_mov_b32_e32 v10, v34
	v_mov_b32_e32 v11, v34
	v_mov_b32_e32 v12, v34
	v_mov_b32_e32 v13, v34
	v_mov_b32_e32 v38, v34
	v_mov_b32_e32 v39, v34
	v_mov_b32_e32 v40, v34
	v_mov_b32_e32 v41, v34
	v_mov_b32_e32 v14, v34
	v_mov_b32_e32 v15, v34
	v_mov_b32_e32 v16, v34
	v_mov_b32_e32 v17, v34
	v_mov_b32_e32 v46, v34
	v_mov_b32_e32 v47, v34
	v_mov_b32_e32 v48, v34
	v_mov_b32_e32 v49, v34
	v_mov_b32_e32 v22, v34
	v_mov_b32_e32 v23, v34
	v_mov_b32_e32 v24, v34
	v_mov_b32_e32 v25, v34
	v_mov_b32_e32 v50, v34
	v_mov_b32_e32 v51, v34
	v_mov_b32_e32 v52, v34
	v_mov_b32_e32 v53, v34
	v_mov_b32_e32 v18, v34
	v_mov_b32_e32 v19, v34
	v_mov_b32_e32 v20, v34
	v_mov_b32_e32 v21, v34
	v_mov_b32_e32 v54, v34
	v_mov_b32_e32 v55, v34
	v_mov_b32_e32 v56, v34
	v_mov_b32_e32 v57, v34
	v_mov_b32_e32 v30, v34
	v_mov_b32_e32 v31, v34
	v_mov_b32_e32 v32, v34
	v_mov_b32_e32 v33, v34
	v_mov_b32_e32 v58, v34
	v_mov_b32_e32 v59, v34
	v_mov_b32_e32 v60, v34
	v_mov_b32_e32 v61, v34
	v_mov_b32_e32 v26, v34
	v_mov_b32_e32 v27, v34
	v_mov_b32_e32 v28, v34
	v_mov_b32_e32 v29, v34
	v_mov_b32_e32 v62, v34
	v_mov_b32_e32 v63, v34
	v_mov_b32_e32 v64, v34
	v_mov_b32_e32 v65, v34
	v_mov_b32_e32 v2, v34
	v_mov_b32_e32 v3, v34
	v_mov_b32_e32 v4, v34
	v_mov_b32_e32 v5, v34
	s_load_dwordx2 s[44:45], s[12:13], 0x0
	v_lshrrev_b32_e32 v253, 5, v131
	v_and_b32_e32 v254, 31, v131
	v_lshlrev_b32_e32 v253, 13, v253
	v_lshl_or_b32 v252, v254, 4, v253
	s_lshl_b32 s46, s22, 13
	s_lshl_b32 s47, s42, 2
	s_add_i32 s46, s46, s47
	s_waitcnt lgkmcnt(0)
	s_add_u32 s44, s44, s46
	s_addc_u32 s45, s45, 0
	global_load_dwordx4 v[180:183], v252, s[44:45]
	s_add_u32 s44, s44, 0x10000
	s_addc_u32 s45, s45, 0
	global_load_dwordx4 v[184:187], v252, s[44:45]
	s_add_u32 s44, s44, 0x10000
	s_addc_u32 s45, s45, 0
	global_load_dwordx4 v[188:191], v252, s[44:45]
	s_add_u32 s44, s44, 0x10000
	s_addc_u32 s45, s45, 0
	global_load_dwordx4 v[196:199], v252, s[44:45]
	s_add_u32 s44, s44, 0x10000
	s_addc_u32 s45, s45, 0
	global_load_dwordx4 v[200:203], v252, s[44:45]
	s_add_u32 s44, s44, 0x10000
	s_addc_u32 s45, s45, 0
	global_load_dwordx4 v[204:207], v252, s[44:45]
	s_add_u32 s44, s44, 0x10000
	s_addc_u32 s45, s45, 0
	global_load_dwordx4 v[212:215], v252, s[44:45]
	s_add_u32 s44, s44, 0x10000
	s_addc_u32 s45, s45, 0
	global_load_dwordx4 v[216:219], v252, s[44:45]
	s_add_u32 s44, s44, 0x10000
	s_addc_u32 s45, s45, 0
	global_load_dwordx4 v[220:223], v252, s[44:45]
	s_add_u32 s44, s44, 0x10000
	s_addc_u32 s45, s45, 0
	global_load_dwordx4 v[224:227], v252, s[44:45]
	s_add_u32 s44, s44, 0x10000
	s_addc_u32 s45, s45, 0
	global_load_dwordx4 v[228:231], v252, s[44:45]
	s_add_u32 s44, s44, 0x10000
	s_addc_u32 s45, s45, 0
	global_load_dwordx4 v[232:235], v252, s[44:45]
	s_add_u32 s44, s44, 0x10000
	s_addc_u32 s45, s45, 0
	global_load_dwordx4 v[236:239], v252, s[44:45]
	s_add_u32 s44, s44, 0x10000
	s_addc_u32 s45, s45, 0
	global_load_dwordx4 v[240:243], v252, s[44:45]
	s_add_u32 s44, s44, 0x10000
	s_addc_u32 s45, s45, 0
	global_load_dwordx4 v[244:247], v252, s[44:45]
	s_add_u32 s44, s44, 0x10000
	s_addc_u32 s45, s45, 0
	global_load_dwordx4 v[248:251], v252, s[44:45]
	s_branch .LBB0_191

.LBB0_193:
	v_and_b32_e32 v0, 64, v74
	v_lshl_or_b32 v66, v76, 2, v77
	s_movk_i32 s24, 0x210
	v_lshl_add_u32 v0, v0, 2, 16
	v_lshlrev_b32_e32 v67, 2, v75
	v_mul_lo_u32 v66, v66, s24
	v_add3_u32 v0, v0, v67, v66
	ds_write2_b32 v0, v34, v6 offset1:16
	ds_write2_b32 v0, v35, v7 offset0:132 offset1:148
	v_add_u32_e32 v6, 0x400, v0
	ds_write2_b32 v6, v36, v8 offset0:8 offset1:24
	ds_write2_b32 v6, v37, v9 offset0:140 offset1:156
	ds_write2_b32 v0, v42, v10 offset0:32 offset1:48
	ds_write2_b32 v0, v43, v11 offset0:164 offset1:180
	ds_write2_b32 v6, v44, v12 offset0:40 offset1:56
	ds_write2_b32 v6, v45, v13 offset0:172 offset1:188
	v_add_u32_e32 v6, 0x2000, v0
	v_add_u32_e32 v7, 0x2400, v0
	ds_write2_b32 v6, v38, v14 offset0:64 offset1:80
	ds_write2_b32 v6, v39, v15 offset0:196 offset1:212
	ds_write2_b32 v7, v40, v16 offset0:72 offset1:88
	ds_write2_b32 v7, v41, v17 offset0:204 offset1:220
	ds_write2_b32 v6, v46, v22 offset0:96 offset1:112
	ds_write2_b32 v6, v47, v23 offset0:228 offset1:244
	ds_write2_b32 v7, v48, v24 offset0:104 offset1:120
	ds_write2_b32 v7, v49, v25 offset0:236 offset1:252
	v_add_u32_e32 v6, 0x4000, v0
	v_add_u32_e32 v7, 0x4400, v0
	v_add_u32_e32 v8, 0x4800, v0
	ds_write2_b32 v6, v50, v18 offset0:128 offset1:144
	ds_write2_b32 v7, v51, v19 offset0:4 offset1:20
	ds_write2_b32 v7, v52, v20 offset0:136 offset1:152
	ds_write2_b32 v8, v53, v21 offset0:12 offset1:28
	ds_write2_b32 v6, v54, v30 offset0:160 offset1:176
	ds_write2_b32 v7, v55, v31 offset0:36 offset1:52
	ds_write2_b32 v7, v56, v32 offset0:168 offset1:184
	ds_write2_b32 v8, v57, v33 offset0:44 offset1:60
	v_add_u32_e32 v6, 0x6000, v0
	v_add_u32_e32 v7, 0x6400, v0
	v_add_u32_e32 v0, 0x6800, v0
	ds_write2_b32 v6, v58, v26 offset0:192 offset1:208
	ds_write2_b32 v7, v59, v27 offset0:68 offset1:84
	ds_write2_b32 v7, v60, v28 offset0:200 offset1:216
	ds_write2_b32 v0, v61, v29 offset0:76 offset1:92
	ds_write2_b32 v6, v62, v2 offset0:224 offset1:240
	ds_write2_b32 v7, v63, v3 offset0:100 offset1:116
	ds_write2_b32 v7, v64, v4 offset0:232 offset1:248
	ds_write2_b32 v0, v65, v5 offset0:108 offset1:124
	s_load_dwordx2 s[44:45], s[12:13], 0x100
	s_load_dwordx2 s[46:47], s[12:13], 0x160
	s_load_dwordx2 s[48:49], s[12:13], 0x1c8
	s_waitcnt vmcnt(0) lgkmcnt(0)
	s_barrier
	s_lshl_b32 s24, s22, 13
	s_lshl_b32 s25, s42, 2
	s_add_i32 s24, s24, s25
	s_add_u32 s44, s44, s24
	s_addc_u32 s45, s45, 0
	s_mul_i32 s24, s22, s81
	s_lshl_b32 s25, s42, 1
	s_add_i32 s24, s24, s25
	s_add_u32 s46, s46, s24
	s_addc_u32 s47, s47, 0
	s_lshl_b32 s24, s22, 2
	s_add_u32 s48, s48, s24
	s_addc_u32 s49, s49, 0
	v_lshrrev_b32_e32 v66, 5, v131
	v_and_b32_e32 v67, 31, v131
	s_movk_i32 s25, 0x210
	v_lshlrev_b32_e32 v68, 4, v67
	v_mad_u32_u24 v69, v66, s25, v68
	v_add_u32_e32 v69, 16, v69
	ds_read_b128 v[2:5], v69
	ds_read_b128 v[6:9], v69 offset:4224
	ds_read_b128 v[10:13], v69 offset:8448
	ds_read_b128 v[14:17], v69 offset:12672
	ds_read_b128 v[18:21], v69 offset:16896
	ds_read_b128 v[22:25], v69 offset:21120
	ds_read_b128 v[26:29], v69 offset:25344
	ds_read_b128 v[30:33], v69 offset:29568
	ds_read_b128 v[34:37], v69 offset:33792
	ds_read_b128 v[38:41], v69 offset:38016
	ds_read_b128 v[42:45], v69 offset:42240
	ds_read_b128 v[46:49], v69 offset:46464
	ds_read_b128 v[50:53], v69 offset:50688
	ds_read_b128 v[54:57], v69 offset:54912
	ds_read_b128 v[58:61], v69 offset:59136
	ds_read_b128 v[62:65], v69 offset:63360
	v_lshlrev_b32_e32 v70, 3, v67
	v_mad_u32_u24 v70, v66, s81, v70
	v_lshlrev_b32_e32 v71, 2, v66
	s_waitcnt lgkmcnt(15)
	v_pk_add_f32 v[2:3], v[2:3], v[180:181]
	v_pk_add_f32 v[4:5], v[4:5], v[182:183]
	global_store_dwordx4 v252, v[2:5], s[44:45]
	v_cvt_pk_bf16_f32 v180, v2, v3
	v_cvt_pk_bf16_f32 v181, v4, v5
	global_store_dwordx2 v70, v[180:181], s[46:47]
	v_mul_f32_e32 v182, v2, v2
	v_fmac_f32_e32 v182, v3, v3
	v_fmac_f32_e32 v182, v4, v4
	v_fmac_f32_e32 v182, v5, v5
	s_add_u32 s44, s44, 0x10000
	s_addc_u32 s45, s45, 0
	s_add_u32 s46, s46, 0x8400
	s_addc_u32 s47, s47, 0
	s_waitcnt lgkmcnt(14)
	v_pk_add_f32 v[6:7], v[6:7], v[184:185]
	v_pk_add_f32 v[8:9], v[8:9], v[186:187]
	global_store_dwordx4 v252, v[6:9], s[44:45]
	v_cvt_pk_bf16_f32 v184, v6, v7
	v_cvt_pk_bf16_f32 v185, v8, v9
	global_store_dwordx2 v70, v[184:185], s[46:47]
	v_mul_f32_e32 v186, v6, v6
	v_fmac_f32_e32 v186, v7, v7
	v_fmac_f32_e32 v186, v8, v8
	v_fmac_f32_e32 v186, v9, v9
	s_add_u32 s44, s44, 0x10000
	s_addc_u32 s45, s45, 0
	s_add_u32 s46, s46, 0x8400
	s_addc_u32 s47, s47, 0
	s_waitcnt lgkmcnt(13)
	v_pk_add_f32 v[10:11], v[10:11], v[188:189]
	v_pk_add_f32 v[12:13], v[12:13], v[190:191]
	global_store_dwordx4 v252, v[10:13], s[44:45]
	v_cvt_pk_bf16_f32 v188, v10, v11
	v_cvt_pk_bf16_f32 v189, v12, v13
	global_store_dwordx2 v70, v[188:189], s[46:47]
	v_mul_f32_e32 v190, v10, v10
	v_fmac_f32_e32 v190, v11, v11
	v_fmac_f32_e32 v190, v12, v12
	v_fmac_f32_e32 v190, v13, v13
	s_add_u32 s44, s44, 0x10000
	s_addc_u32 s45, s45, 0
	s_add_u32 s46, s46, 0x8400
	s_addc_u32 s47, s47, 0
	s_waitcnt lgkmcnt(12)
	v_pk_add_f32 v[14:15], v[14:15], v[196:197]
	v_pk_add_f32 v[16:17], v[16:17], v[198:199]
	global_store_dwordx4 v252, v[14:17], s[44:45]
	v_cvt_pk_bf16_f32 v196, v14, v15
	v_cvt_pk_bf16_f32 v197, v16, v17
	global_store_dwordx2 v70, v[196:197], s[46:47]
	v_mul_f32_e32 v198, v14, v14
	v_fmac_f32_e32 v198, v15, v15
	v_fmac_f32_e32 v198, v16, v16
	v_fmac_f32_e32 v198, v17, v17
	s_add_u32 s44, s44, 0x10000
	s_addc_u32 s45, s45, 0
	s_add_u32 s46, s46, 0x8400
	s_addc_u32 s47, s47, 0
	s_waitcnt lgkmcnt(11)
	v_pk_add_f32 v[18:19], v[18:19], v[200:201]
	v_pk_add_f32 v[20:21], v[20:21], v[202:203]
	global_store_dwordx4 v252, v[18:21], s[44:45]
	v_cvt_pk_bf16_f32 v200, v18, v19
	v_cvt_pk_bf16_f32 v201, v20, v21
	global_store_dwordx2 v70, v[200:201], s[46:47]
	v_mul_f32_e32 v202, v18, v18
	v_fmac_f32_e32 v202, v19, v19
	v_fmac_f32_e32 v202, v20, v20
	v_fmac_f32_e32 v202, v21, v21
	s_add_u32 s44, s44, 0x10000
	s_addc_u32 s45, s45, 0
	s_add_u32 s46, s46, 0x8400
	s_addc_u32 s47, s47, 0
	s_waitcnt lgkmcnt(10)
	v_pk_add_f32 v[22:23], v[22:23], v[204:205]
	v_pk_add_f32 v[24:25], v[24:25], v[206:207]
	global_store_dwordx4 v252, v[22:25], s[44:45]
	v_cvt_pk_bf16_f32 v204, v22, v23
	v_cvt_pk_bf16_f32 v205, v24, v25
	global_store_dwordx2 v70, v[204:205], s[46:47]
	v_mul_f32_e32 v206, v22, v22
	v_fmac_f32_e32 v206, v23, v23
	v_fmac_f32_e32 v206, v24, v24
	v_fmac_f32_e32 v206, v25, v25
	s_add_u32 s44, s44, 0x10000
	s_addc_u32 s45, s45, 0
	s_add_u32 s46, s46, 0x8400
	s_addc_u32 s47, s47, 0
	s_waitcnt lgkmcnt(9)
	v_pk_add_f32 v[26:27], v[26:27], v[212:213]
	v_pk_add_f32 v[28:29], v[28:29], v[214:215]
	global_store_dwordx4 v252, v[26:29], s[44:45]
	v_cvt_pk_bf16_f32 v212, v26, v27
	v_cvt_pk_bf16_f32 v213, v28, v29
	global_store_dwordx2 v70, v[212:213], s[46:47]
	v_mul_f32_e32 v214, v26, v26
	v_fmac_f32_e32 v214, v27, v27
	v_fmac_f32_e32 v214, v28, v28
	v_fmac_f32_e32 v214, v29, v29
	s_add_u32 s44, s44, 0x10000
	s_addc_u32 s45, s45, 0
	s_add_u32 s46, s46, 0x8400
	s_addc_u32 s47, s47, 0
	s_waitcnt lgkmcnt(8)
	v_pk_add_f32 v[30:31], v[30:31], v[216:217]
	v_pk_add_f32 v[32:33], v[32:33], v[218:219]
	global_store_dwordx4 v252, v[30:33], s[44:45]
	v_cvt_pk_bf16_f32 v216, v30, v31
	v_cvt_pk_bf16_f32 v217, v32, v33
	global_store_dwordx2 v70, v[216:217], s[46:47]
	v_mul_f32_e32 v218, v30, v30
	v_fmac_f32_e32 v218, v31, v31
	v_fmac_f32_e32 v218, v32, v32
	v_fmac_f32_e32 v218, v33, v33
	s_add_u32 s44, s44, 0x10000
	s_addc_u32 s45, s45, 0
	s_add_u32 s46, s46, 0x8400
	s_addc_u32 s47, s47, 0
	s_waitcnt lgkmcnt(7)
	v_pk_add_f32 v[34:35], v[34:35], v[220:221]
	v_pk_add_f32 v[36:37], v[36:37], v[222:223]
	global_store_dwordx4 v252, v[34:37], s[44:45]
	v_cvt_pk_bf16_f32 v220, v34, v35
	v_cvt_pk_bf16_f32 v221, v36, v37
	global_store_dwordx2 v70, v[220:221], s[46:47]
	v_mul_f32_e32 v222, v34, v34
	v_fmac_f32_e32 v222, v35, v35
	v_fmac_f32_e32 v222, v36, v36
	v_fmac_f32_e32 v222, v37, v37
	s_add_u32 s44, s44, 0x10000
	s_addc_u32 s45, s45, 0
	s_add_u32 s46, s46, 0x8400
	s_addc_u32 s47, s47, 0
	s_waitcnt lgkmcnt(6)
	v_pk_add_f32 v[38:39], v[38:39], v[224:225]
	v_pk_add_f32 v[40:41], v[40:41], v[226:227]
	global_store_dwordx4 v252, v[38:41], s[44:45]
	v_cvt_pk_bf16_f32 v224, v38, v39
	v_cvt_pk_bf16_f32 v225, v40, v41
	global_store_dwordx2 v70, v[224:225], s[46:47]
	v_mul_f32_e32 v226, v38, v38
	v_fmac_f32_e32 v226, v39, v39
	v_fmac_f32_e32 v226, v40, v40
	v_fmac_f32_e32 v226, v41, v41
	s_add_u32 s44, s44, 0x10000
	s_addc_u32 s45, s45, 0
	s_add_u32 s46, s46, 0x8400
	s_addc_u32 s47, s47, 0
	s_waitcnt lgkmcnt(5)
	v_pk_add_f32 v[42:43], v[42:43], v[228:229]
	v_pk_add_f32 v[44:45], v[44:45], v[230:231]
	global_store_dwordx4 v252, v[42:45], s[44:45]
	v_cvt_pk_bf16_f32 v228, v42, v43
	v_cvt_pk_bf16_f32 v229, v44, v45
	global_store_dwordx2 v70, v[228:229], s[46:47]
	v_mul_f32_e32 v230, v42, v42
	v_fmac_f32_e32 v230, v43, v43
	v_fmac_f32_e32 v230, v44, v44
	v_fmac_f32_e32 v230, v45, v45
	s_add_u32 s44, s44, 0x10000
	s_addc_u32 s45, s45, 0
	s_add_u32 s46, s46, 0x8400
	s_addc_u32 s47, s47, 0
	s_waitcnt lgkmcnt(4)
	v_pk_add_f32 v[46:47], v[46:47], v[232:233]
	v_pk_add_f32 v[48:49], v[48:49], v[234:235]
	global_store_dwordx4 v252, v[46:49], s[44:45]
	v_cvt_pk_bf16_f32 v232, v46, v47
	v_cvt_pk_bf16_f32 v233, v48, v49
	global_store_dwordx2 v70, v[232:233], s[46:47]
	v_mul_f32_e32 v234, v46, v46
	v_fmac_f32_e32 v234, v47, v47
	v_fmac_f32_e32 v234, v48, v48
	v_fmac_f32_e32 v234, v49, v49
	s_add_u32 s44, s44, 0x10000
	s_addc_u32 s45, s45, 0
	s_add_u32 s46, s46, 0x8400
	s_addc_u32 s47, s47, 0
	s_waitcnt lgkmcnt(3)
	v_pk_add_f32 v[50:51], v[50:51], v[236:237]
	v_pk_add_f32 v[52:53], v[52:53], v[238:239]
	global_store_dwordx4 v252, v[50:53], s[44:45]
	v_cvt_pk_bf16_f32 v236, v50, v51
	v_cvt_pk_bf16_f32 v237, v52, v53
	global_store_dwordx2 v70, v[236:237], s[46:47]
	v_mul_f32_e32 v238, v50, v50
	v_fmac_f32_e32 v238, v51, v51
	v_fmac_f32_e32 v238, v52, v52
	v_fmac_f32_e32 v238, v53, v53
	s_add_u32 s44, s44, 0x10000
	s_addc_u32 s45, s45, 0
	s_add_u32 s46, s46, 0x8400
	s_addc_u32 s47, s47, 0
	s_waitcnt lgkmcnt(2)
	v_pk_add_f32 v[54:55], v[54:55], v[240:241]
	v_pk_add_f32 v[56:57], v[56:57], v[242:243]
	global_store_dwordx4 v252, v[54:57], s[44:45]
	v_cvt_pk_bf16_f32 v240, v54, v55
	v_cvt_pk_bf16_f32 v241, v56, v57
	global_store_dwordx2 v70, v[240:241], s[46:47]
	v_mul_f32_e32 v242, v54, v54
	v_fmac_f32_e32 v242, v55, v55
	v_fmac_f32_e32 v242, v56, v56
	v_fmac_f32_e32 v242, v57, v57
	s_add_u32 s44, s44, 0x10000
	s_addc_u32 s45, s45, 0
	s_add_u32 s46, s46, 0x8400
	s_addc_u32 s47, s47, 0
	s_waitcnt lgkmcnt(1)
	v_pk_add_f32 v[58:59], v[58:59], v[244:245]
	v_pk_add_f32 v[60:61], v[60:61], v[246:247]
	global_store_dwordx4 v252, v[58:61], s[44:45]
	v_cvt_pk_bf16_f32 v244, v58, v59
	v_cvt_pk_bf16_f32 v245, v60, v61
	global_store_dwordx2 v70, v[244:245], s[46:47]
	v_mul_f32_e32 v246, v58, v58
	v_fmac_f32_e32 v246, v59, v59
	v_fmac_f32_e32 v246, v60, v60
	v_fmac_f32_e32 v246, v61, v61
	s_add_u32 s44, s44, 0x10000
	s_addc_u32 s45, s45, 0
	s_add_u32 s46, s46, 0x8400
	s_addc_u32 s47, s47, 0
	s_waitcnt lgkmcnt(0)
	v_pk_add_f32 v[62:63], v[62:63], v[248:249]
	v_pk_add_f32 v[64:65], v[64:65], v[250:251]
	global_store_dwordx4 v252, v[62:65], s[44:45]
	v_cvt_pk_bf16_f32 v248, v62, v63
	v_cvt_pk_bf16_f32 v249, v64, v65
	global_store_dwordx2 v70, v[248:249], s[46:47]
	v_mul_f32_e32 v250, v62, v62
	v_fmac_f32_e32 v250, v63, v63
	v_fmac_f32_e32 v250, v64, v64
	v_fmac_f32_e32 v250, v65, v65
	s_nop 1
	v_add_f32_dpp v182, v182, v182 quad_perm:[1,0,3,2] row_mask:0xf bank_mask:0xf
	v_add_f32_dpp v186, v186, v186 quad_perm:[1,0,3,2] row_mask:0xf bank_mask:0xf
	v_add_f32_dpp v190, v190, v190 quad_perm:[1,0,3,2] row_mask:0xf bank_mask:0xf
	v_add_f32_dpp v198, v198, v198 quad_perm:[1,0,3,2] row_mask:0xf bank_mask:0xf
	v_add_f32_dpp v202, v202, v202 quad_perm:[1,0,3,2] row_mask:0xf bank_mask:0xf
	v_add_f32_dpp v206, v206, v206 quad_perm:[1,0,3,2] row_mask:0xf bank_mask:0xf
	v_add_f32_dpp v214, v214, v214 quad_perm:[1,0,3,2] row_mask:0xf bank_mask:0xf
	v_add_f32_dpp v218, v218, v218 quad_perm:[1,0,3,2] row_mask:0xf bank_mask:0xf
	v_add_f32_dpp v222, v222, v222 quad_perm:[1,0,3,2] row_mask:0xf bank_mask:0xf
	v_add_f32_dpp v226, v226, v226 quad_perm:[1,0,3,2] row_mask:0xf bank_mask:0xf
	v_add_f32_dpp v230, v230, v230 quad_perm:[1,0,3,2] row_mask:0xf bank_mask:0xf
	v_add_f32_dpp v234, v234, v234 quad_perm:[1,0,3,2] row_mask:0xf bank_mask:0xf
	v_add_f32_dpp v238, v238, v238 quad_perm:[1,0,3,2] row_mask:0xf bank_mask:0xf
	v_add_f32_dpp v242, v242, v242 quad_perm:[1,0,3,2] row_mask:0xf bank_mask:0xf
	v_add_f32_dpp v246, v246, v246 quad_perm:[1,0,3,2] row_mask:0xf bank_mask:0xf
	v_add_f32_dpp v250, v250, v250 quad_perm:[1,0,3,2] row_mask:0xf bank_mask:0xf
	v_add_f32_dpp v182, v182, v182 quad_perm:[2,3,0,1] row_mask:0xf bank_mask:0xf
	v_add_f32_dpp v186, v186, v186 quad_perm:[2,3,0,1] row_mask:0xf bank_mask:0xf
	v_add_f32_dpp v190, v190, v190 quad_perm:[2,3,0,1] row_mask:0xf bank_mask:0xf
	v_add_f32_dpp v198, v198, v198 quad_perm:[2,3,0,1] row_mask:0xf bank_mask:0xf
	v_add_f32_dpp v202, v202, v202 quad_perm:[2,3,0,1] row_mask:0xf bank_mask:0xf
	v_add_f32_dpp v206, v206, v206 quad_perm:[2,3,0,1] row_mask:0xf bank_mask:0xf
	v_add_f32_dpp v214, v214, v214 quad_perm:[2,3,0,1] row_mask:0xf bank_mask:0xf
	v_add_f32_dpp v218, v218, v218 quad_perm:[2,3,0,1] row_mask:0xf bank_mask:0xf
	v_add_f32_dpp v222, v222, v222 quad_perm:[2,3,0,1] row_mask:0xf bank_mask:0xf
	v_add_f32_dpp v226, v226, v226 quad_perm:[2,3,0,1] row_mask:0xf bank_mask:0xf
	v_add_f32_dpp v230, v230, v230 quad_perm:[2,3,0,1] row_mask:0xf bank_mask:0xf
	v_add_f32_dpp v234, v234, v234 quad_perm:[2,3,0,1] row_mask:0xf bank_mask:0xf
	v_add_f32_dpp v238, v238, v238 quad_perm:[2,3,0,1] row_mask:0xf bank_mask:0xf
	v_add_f32_dpp v242, v242, v242 quad_perm:[2,3,0,1] row_mask:0xf bank_mask:0xf
	v_add_f32_dpp v246, v246, v246 quad_perm:[2,3,0,1] row_mask:0xf bank_mask:0xf
	v_add_f32_dpp v250, v250, v250 quad_perm:[2,3,0,1] row_mask:0xf bank_mask:0xf
	v_add_f32_dpp v182, v182, v182 row_half_mirror row_mask:0xf bank_mask:0xf
	v_add_f32_dpp v186, v186, v186 row_half_mirror row_mask:0xf bank_mask:0xf
	v_add_f32_dpp v190, v190, v190 row_half_mirror row_mask:0xf bank_mask:0xf
	v_add_f32_dpp v198, v198, v198 row_half_mirror row_mask:0xf bank_mask:0xf
	v_add_f32_dpp v202, v202, v202 row_half_mirror row_mask:0xf bank_mask:0xf
	v_add_f32_dpp v206, v206, v206 row_half_mirror row_mask:0xf bank_mask:0xf
	v_add_f32_dpp v214, v214, v214 row_half_mirror row_mask:0xf bank_mask:0xf
	v_add_f32_dpp v218, v218, v218 row_half_mirror row_mask:0xf bank_mask:0xf
	v_add_f32_dpp v222, v222, v222 row_half_mirror row_mask:0xf bank_mask:0xf
	v_add_f32_dpp v226, v226, v226 row_half_mirror row_mask:0xf bank_mask:0xf
	v_add_f32_dpp v230, v230, v230 row_half_mirror row_mask:0xf bank_mask:0xf
	v_add_f32_dpp v234, v234, v234 row_half_mirror row_mask:0xf bank_mask:0xf
	v_add_f32_dpp v238, v238, v238 row_half_mirror row_mask:0xf bank_mask:0xf
	v_add_f32_dpp v242, v242, v242 row_half_mirror row_mask:0xf bank_mask:0xf
	v_add_f32_dpp v246, v246, v246 row_half_mirror row_mask:0xf bank_mask:0xf
	v_add_f32_dpp v250, v250, v250 row_half_mirror row_mask:0xf bank_mask:0xf
	v_add_f32_dpp v182, v182, v182 row_mirror row_mask:0xf bank_mask:0xf
	v_add_f32_dpp v186, v186, v186 row_mirror row_mask:0xf bank_mask:0xf
	v_add_f32_dpp v190, v190, v190 row_mirror row_mask:0xf bank_mask:0xf
	v_add_f32_dpp v198, v198, v198 row_mirror row_mask:0xf bank_mask:0xf
	v_add_f32_dpp v202, v202, v202 row_mirror row_mask:0xf bank_mask:0xf
	v_add_f32_dpp v206, v206, v206 row_mirror row_mask:0xf bank_mask:0xf
	v_add_f32_dpp v214, v214, v214 row_mirror row_mask:0xf bank_mask:0xf
	v_add_f32_dpp v218, v218, v218 row_mirror row_mask:0xf bank_mask:0xf
	v_add_f32_dpp v222, v222, v222 row_mirror row_mask:0xf bank_mask:0xf
	v_add_f32_dpp v226, v226, v226 row_mirror row_mask:0xf bank_mask:0xf
	v_add_f32_dpp v230, v230, v230 row_mirror row_mask:0xf bank_mask:0xf
	v_add_f32_dpp v234, v234, v234 row_mirror row_mask:0xf bank_mask:0xf
	v_add_f32_dpp v238, v238, v238 row_mirror row_mask:0xf bank_mask:0xf
	v_add_f32_dpp v242, v242, v242 row_mirror row_mask:0xf bank_mask:0xf
	v_add_f32_dpp v246, v246, v246 row_mirror row_mask:0xf bank_mask:0xf
	v_add_f32_dpp v250, v250, v250 row_mirror row_mask:0xf bank_mask:0xf
	v_add_f32_dpp v182, v182, v182 row_bcast:15 row_mask:0xa bank_mask:0xf
	v_add_f32_dpp v186, v186, v186 row_bcast:15 row_mask:0xa bank_mask:0xf
	v_add_f32_dpp v190, v190, v190 row_bcast:15 row_mask:0xa bank_mask:0xf
	v_add_f32_dpp v198, v198, v198 row_bcast:15 row_mask:0xa bank_mask:0xf
	v_add_f32_dpp v202, v202, v202 row_bcast:15 row_mask:0xa bank_mask:0xf
	v_add_f32_dpp v206, v206, v206 row_bcast:15 row_mask:0xa bank_mask:0xf
	v_add_f32_dpp v214, v214, v214 row_bcast:15 row_mask:0xa bank_mask:0xf
	v_add_f32_dpp v218, v218, v218 row_bcast:15 row_mask:0xa bank_mask:0xf
	v_add_f32_dpp v222, v222, v222 row_bcast:15 row_mask:0xa bank_mask:0xf
	v_add_f32_dpp v226, v226, v226 row_bcast:15 row_mask:0xa bank_mask:0xf
	v_add_f32_dpp v230, v230, v230 row_bcast:15 row_mask:0xa bank_mask:0xf
	v_add_f32_dpp v234, v234, v234 row_bcast:15 row_mask:0xa bank_mask:0xf
	v_add_f32_dpp v238, v238, v238 row_bcast:15 row_mask:0xa bank_mask:0xf
	v_add_f32_dpp v242, v242, v242 row_bcast:15 row_mask:0xa bank_mask:0xf
	v_add_f32_dpp v246, v246, v246 row_bcast:15 row_mask:0xa bank_mask:0xf
	v_add_f32_dpp v250, v250, v250 row_bcast:15 row_mask:0xa bank_mask:0xf
	s_mov_b32 exec_lo, 0x10000
	s_mov_b32 exec_hi, 0x10000
	global_atomic_add_f32 v71, v182, s[48:49]
	global_atomic_add_f32 v71, v186, s[48:49] offset:32
	global_atomic_add_f32 v71, v190, s[48:49] offset:64
	global_atomic_add_f32 v71, v198, s[48:49] offset:96
	global_atomic_add_f32 v71, v202, s[48:49] offset:128
	global_atomic_add_f32 v71, v206, s[48:49] offset:160
	global_atomic_add_f32 v71, v214, s[48:49] offset:192
	global_atomic_add_f32 v71, v218, s[48:49] offset:224
	global_atomic_add_f32 v71, v222, s[48:49] offset:256
	global_atomic_add_f32 v71, v226, s[48:49] offset:288
	global_atomic_add_f32 v71, v230, s[48:49] offset:320
	global_atomic_add_f32 v71, v234, s[48:49] offset:352
	global_atomic_add_f32 v71, v238, s[48:49] offset:384
	global_atomic_add_f32 v71, v242, s[48:49] offset:416
	global_atomic_add_f32 v71, v246, s[48:49] offset:448
	global_atomic_add_f32 v71, v250, s[48:49] offset:480
	s_mov_b64 exec, -1
	s_branch .LBB0_188

	.amdhsa_kernel _Z10hymba_mega6Params
		.amdhsa_group_segment_fixed_size 16
		.amdhsa_private_segment_fixed_size 0
		.amdhsa_kernarg_size 768
		.amdhsa_user_sgpr_count 2
		.amdhsa_user_sgpr_dispatch_ptr 0
		.amdhsa_user_sgpr_queue_ptr 0
		.amdhsa_user_sgpr_kernarg_segment_ptr 1
		.amdhsa_user_sgpr_dispatch_id 0
		.amdhsa_user_sgpr_kernarg_preload_length 0
		.amdhsa_user_sgpr_kernarg_preload_offset 0
		.amdhsa_user_sgpr_private_segment_size 0
		.amdhsa_uses_dynamic_stack 0
		.amdhsa_enable_private_segment 0
		.amdhsa_system_sgpr_workgroup_id_x 1
		.amdhsa_system_sgpr_workgroup_id_y 0
		.amdhsa_system_sgpr_workgroup_id_z 0
		.amdhsa_system_sgpr_workgroup_info 0
		.amdhsa_system_vgpr_workitem_id 2
		.amdhsa_next_free_vgpr 256
		.amdhsa_next_free_sgpr 100
		.amdhsa_accum_offset 256
		.amdhsa_reserve_vcc 1
		.amdhsa_float_round_mode_32 0
		.amdhsa_float_round_mode_16_64 0
		.amdhsa_float_denorm_mode_32 3
		.amdhsa_float_denorm_mode_16_64 3
		.amdhsa_dx10_clamp 1
		.amdhsa_ieee_mode 1
		.amdhsa_fp16_overflow 0
		.amdhsa_tg_split 0
		.amdhsa_exception_fp_ieee_invalid_op 0
		.amdhsa_exception_fp_denorm_src 0
		.amdhsa_exception_fp_ieee_div_zero 0
		.amdhsa_exception_fp_ieee_overflow 0
		.amdhsa_exception_fp_ieee_underflow 0
		.amdhsa_exception_fp_ieee_inexact 0
		.amdhsa_exception_int_div_zero 0
	.end_amdhsa_kernel

amdhsa.kernels:
  - .agpr_count:     0
    .args:
      - .offset:         0
        .size:           512
        .value_kind:     by_value
      - .offset:         512
        .size:           4
        .value_kind:     hidden_block_count_x
      - .offset:         516
        .size:           4
        .value_kind:     hidden_block_count_y
      - .offset:         520
        .size:           4
        .value_kind:     hidden_block_count_z
      - .offset:         524
        .size:           2
        .value_kind:     hidden_group_size_x
      - .offset:         526
        .size:           2
        .value_kind:     hidden_group_size_y
      - .offset:         528
        .size:           2
        .value_kind:     hidden_group_size_z
      - .offset:         530
        .size:           2
        .value_kind:     hidden_remainder_x
      - .offset:         532
        .size:           2
        .value_kind:     hidden_remainder_y
      - .offset:         534
        .size:           2
        .value_kind:     hidden_remainder_z
      - .offset:         552
        .size:           8
        .value_kind:     hidden_global_offset_x
      - .offset:         560
        .size:           8
        .value_kind:     hidden_global_offset_y
      - .offset:         568
        .size:           8
        .value_kind:     hidden_global_offset_z
      - .offset:         576
        .size:           2
        .value_kind:     hidden_grid_dims
      - .offset:         600
        .size:           8
        .value_kind:     hidden_multigrid_sync_arg
      - .offset:         632
        .size:           4
        .value_kind:     hidden_dynamic_lds_size
    .group_segment_fixed_size: 16
    .kernarg_segment_align: 8
    .kernarg_segment_size: 768
    .language:       OpenCL C
    .language_version:
      - 2
      - 0
    .max_flat_workgroup_size: 256
    .name:           _Z10hymba_mega6Params
    .private_segment_fixed_size: 0
    .sgpr_count:     106
    .sgpr_spill_count: 110
    .symbol:         _Z10hymba_mega6Params.kd
    .uniform_work_group_size: 1
    .uses_dynamic_stack: false
    .vgpr_count:     256
    .vgpr_spill_count: 0
    .wavefront_size: 64
